# w_in epilogue: Q tiles get straight-line paths per wave parity; rope table quads loaded once per 16-row block, together
# baseline (speedup 1.0000x reference)
; __device__ __forceinline__ float shx16(float v, int odd  ) { const unsigned x = __builtin_bit_cast(unsigned, v); auto r = __builtin_amdgcn_permlane16_swap(x, x, false, false); return __builtin_bit_cast(float, odd ? r[0] : r[1]); }
; __device__ __forceinline__ void st_bf4(bf16_t* p, const f32x4 v) { u32x2 w; w.x = cvt_pk_bf16(v[0], v[1]); w.y = cvt_pk_bf16(v[2], v[3]); *(u32x2*)p = w; }
;     __device__ __forceinline__ void operator()(const f32x4 (&acc)[2][2][4][2], const Unit& u, int wr, int wc, int fr, int fq) const {
;         const int pn = u.pn;
; #pragma unroll
;         for (int ai = 0; ai < 2; ++ai)
; #pragma unroll
;             for (int m = 0; m < 4; ++m) { const int row = u.pm * 256 + ai * 128 + wr * 64 + m * 16 + fr;
; #pragma unroll
;                 for (int bj = 0; bj < 2; ++bj)
; #pragma unroll
;                     for (int n = 0; n < 2; ++n) { const int tc = bj * 128 + wc * 32 + 8 * fq + 4 * n; f32x4 v = acc[ai][bj][m][n];
;                         if (pn < 2) { *(f32x4*)(XA + (size_t)row * 512 + pn * 256 + tc) = v; }
;                         else if (pn <= 4) {
;                             const bool isv = (pn == 4 && bj == 1);
;                             if (!isv && (wc & 1) == 0) {
;                                 const int tix = row < cfg::MP ? (row & 2047) : 2048 + (row & 3);
;                                 const f32x4 cs = *(const f32x4*)(ropec + tix * 8 + 4 * n), sn = *(const f32x4*)(ropes + tix * 8 + 4 * n);
; #pragma unroll
;                                 for (int i = 0; i < 4; ++i) { const float p = shx16(v[i], fq & 1); const float rv = v[i] * cs[i] + (fq == 0 ? -p : p) * sn[i]; v[i] = fq < 2 ? rv : v[i]; }
;                             }
;                             if (pn < 4) st_bf4(Q + (size_t)row * 512 + (pn - 2) * 256 + tc, v);
.LBB0_1030:
	s_lshl_b32 s53, s0, 8
	v_readlane_b32 s0, v254, 56
	s_add_i32 s53, s53, s0
	s_cmp_gt_i32 s14, 1
	s_cselect_b64 s[70:71], -1, 0
	s_cmp_gt_u32 s14, 4
	s_cselect_b64 s[78:79], -1, 0
	s_cmp_gt_u32 s14, 6
	s_cselect_b64 s[90:91], -1, 0
	s_lshl_b32 s0, s14, 8
	s_add_i32 s56, s0, 0xfffff900
	s_cmp_lg_u32 s14, 4
	v_or_b32_e32 v172, s53, v143
	s_cselect_b64 s[28:29], -1, 0
	s_cmp_eq_u32 s14, 4
	v_mad_i64_i32 v[180:181], s[14:15], v172, s61, 0
	s_movk_i32 s14, 0x3fff
	s_nop 0
	v_cmp_lt_i32_e64 s[20:21], s14, v172
	v_mov_b32_e32 v96, 0x7cf
	s_movk_i32 s14, 0x4000
	v_bitop3_b32 v96, s53, v96, v143 bitop3:0xc8
	v_cmp_gt_i32_e32 vcc, s14, v172
	s_movk_i32 s14, 0x77f
	v_cmp_lt_u32_e64 s[18:19], s14, v96
	v_cndmask_b32_e32 v130, v151, v96, vcc
	v_add_u32_e32 v96, 0xfffff880, v96
	v_ashrrev_i32_e32 v173, 31, v172
	v_lshlrev_b32_e32 v203, 3, v130
	v_add_u32_e32 v130, 0xffffc000, v172
	v_lshlrev_b64 v[182:183], 7, v[96:97]
	s_mov_b64 s[14:15], 0x1080000
	s_mov_b32 s1, s57
	s_cselect_b64 s[96:97], -1, 0
	s_ashr_i32 s75, s53, 11
	v_lshlrev_b64 v[178:179], 11, v[172:173]
	v_lshlrev_b64 v[176:177], 8, v[172:173]
	v_lshrrev_b32_e32 v202, 2, v130
	v_lshlrev_b64 v[174:175], 10, v[172:173]
	v_lshl_add_u64 v[184:185], v[182:183], 0, s[14:15]
	s_mov_b64 s[14:15], -1
	s_and_b64 vcc, exec, s[90:91]
	s_cbranch_vccnz .Lsp_gt
	s_and_b64 vcc, exec, s[78:79]
	s_cbranch_vccnz .Lsp_u
	s_and_b64 vcc, exec, s[70:71]
	s_cbranch_vccz .Lsp_xa
	s_and_b64 vcc, exec, s[28:29]
	s_cbranch_vccz .Lsp_notq
	s_and_b64 vcc, exec, s[76:77]
	s_cbranch_vccnz .Lsp_q1
	s_branch .Lsp_q0
.Lsp_notq:
	s_and_b64 vcc, exec, s[70:71]
	s_cbranch_vccz .LBB0_1045
	s_and_b64 vcc, exec, s[78:79]
	s_cbranch_vccz .LBB0_1037
	s_and_b64 vcc, exec, s[90:91]
	s_cbranch_vccz .LBB0_1034
	v_mul_f32_e32 v96, 0xbfb8aa3b, v126
	v_exp_f32_e32 v96, v96
	v_mul_f32_e32 v130, 0xbfb8aa3b, v127
	v_exp_f32_e32 v130, v130
	v_mul_f32_e32 v131, 0xbfb8aa3b, v129
	v_add_f32_e32 v96, 1.0, v96
	v_rcp_f32_e32 v132, v96
	v_mul_f32_e32 v96, 0xbfb8aa3b, v128
	v_exp_f32_e32 v96, v96
	v_exp_f32_e32 v131, v131
	v_add_f32_e32 v130, 1.0, v130
	v_rcp_f32_e32 v133, v130
	v_add_f32_e32 v96, 1.0, v96
	v_rcp_f32_e32 v146, v96
	v_add_f32_e32 v96, 1.0, v131
	v_lshl_add_u64 v[130:131], s[54:55], 0, v[180:181]
	v_rcp_f32_e32 v147, v96
	v_lshl_add_u64 v[130:131], s[56:57], 1, v[130:131]
	v_lshlrev_b32_e32 v96, 1, v142
	v_lshl_add_u64 v[130:131], v[130:131], 0, v[96:97]
	v_cvt_pk_bf16_f32 v190, v132, v133
	v_cvt_pk_bf16_f32 v191, v146, v147
	s_mov_b64 s[14:15], 0

; __device__ __forceinline__ float shx16(float v, int odd  ) { const unsigned x = __builtin_bit_cast(unsigned, v); auto r = __builtin_amdgcn_permlane16_swap(x, x, false, false); return __builtin_bit_cast(float, odd ? r[0] : r[1]); }
; __device__ __forceinline__ void st_bf4(bf16_t* p, const f32x4 v) { u32x2 w; w.x = cvt_pk_bf16(v[0], v[1]); w.y = cvt_pk_bf16(v[2], v[3]); *(u32x2*)p = w; }
;     __device__ __forceinline__ void operator()(const f32x4 (&acc)[2][2][4][2], const Unit& u, int wr, int wc, int fr, int fq) const {
;     ...
;                     for (int n = 0; n < 2; ++n) { const int tc = bj * 128 + wc * 32 + 8 * fq + 4 * n; f32x4 v = acc[ai][bj][m][n];
;                         if (pn < 2) { *(f32x4*)(XA + (size_t)row * 512 + pn * 256 + tc) = v; }
;                         else if (pn <= 4) {
;                             const bool isv = (pn == 4 && bj == 1);
;                             if (!isv && (wc & 1) == 0) {
;                                 const int tix = row < cfg::MP ? (row & 2047) : 2048 + (row & 3);
;                                 const f32x4 cs = *(const f32x4*)(ropec + tix * 8 + 4 * n), sn = *(const f32x4*)(ropes + tix * 8 + 4 * n);
; #pragma unroll
;                                 for (int i = 0; i < 4; ++i) { const float p = shx16(v[i], fq & 1); const float rv = v[i] * cs[i] + (fq == 0 ? -p : p) * sn[i]; v[i] = fq < 2 ? rv : v[i]; }
;                             }
;                             if (pn < 4) st_bf4(Q + (size_t)row * 512 + (pn - 2) * 256 + tc, v);
.Lsp_q0:
	s_nop 7
	v_lshlrev_b32_e32 v96, 2, v203
	global_load_dwordx4 v[208:211], v96, s[44:45]
	global_load_dwordx4 v[212:215], v96, s[4:5]
	global_load_dwordx4 v[216:219], v96, s[44:45] offset:16
	global_load_dwordx4 v[220:223], v96, s[4:5] offset:16
	v_mov_b32_e32 v96, v126
	v_mov_b32_e32 v146, v126
	s_nop 1
	v_permlane16_swap_b32_e32 v96, v146
	v_cndmask_b32_e64 v96, v96, v146, s[6:7]
	v_cndmask_b32_e64 v147, v96, -v96, s[10:11]
	v_mov_b32_e32 v148, v126
	s_waitcnt vmcnt(2)
	v_mov_b32_e32 v146, v208
	v_mov_b32_e32 v149, v212
	v_pk_mul_f32 v[146:147], v[148:149], v[146:147]
	v_mov_b32_e32 v186, v127
	v_add_f32_e32 v96, v146, v147
	v_cndmask_b32_e64 v130, v126, v96, s[8:9]
	v_mov_b32_e32 v96, v127
	v_mov_b32_e32 v146, v127
	s_nop 1
	v_permlane16_swap_b32_e32 v96, v146
	v_cndmask_b32_e64 v96, v96, v146, s[6:7]
	v_cndmask_b32_e64 v147, v96, -v96, s[10:11]
	v_mov_b32_e32 v146, v209
	v_mov_b32_e32 v187, v213
	v_pk_mul_f32 v[146:147], v[186:187], v[146:147]
	v_mov_b32_e32 v148, v128
	v_add_f32_e32 v96, v146, v147
	v_cndmask_b32_e64 v131, v127, v96, s[8:9]
	v_mov_b32_e32 v96, v128
	v_mov_b32_e32 v146, v128
	s_nop 1
	v_permlane16_swap_b32_e32 v96, v146
	v_cndmask_b32_e64 v96, v96, v146, s[6:7]
	v_cndmask_b32_e64 v147, v96, -v96, s[10:11]
	v_mov_b32_e32 v149, v214
	v_mov_b32_e32 v146, v210
	v_pk_mul_f32 v[146:147], v[148:149], v[146:147]
	v_mov_b32_e32 v188, v129
	v_add_f32_e32 v96, v146, v147
	v_cndmask_b32_e64 v132, v128, v96, s[8:9]
	v_mov_b32_e32 v96, v129
	v_mov_b32_e32 v146, v129
	s_nop 1
	v_permlane16_swap_b32_e32 v96, v146
	v_cndmask_b32_e64 v96, v96, v146, s[6:7]
	v_cndmask_b32_e64 v147, v96, -v96, s[10:11]
	v_mov_b32_e32 v146, v211
	v_mov_b32_e32 v189, v215
	v_pk_mul_f32 v[146:147], v[188:189], v[146:147]
	v_mov_b32_e32 v173, v130
	v_add_f32_e32 v96, v146, v147
	v_cndmask_b32_e64 v133, v129, v96, s[8:9]
	v_mov_b32_e32 v205, v131
	v_mov_b32_e32 v204, v132
	v_mov_b32_e32 v206, v133
	v_lshl_add_u64 v[130:131], s[82:83], 0, v[174:175]
	v_lshl_add_u64 v[130:131], s[0:1], 1, v[130:131]
	v_lshlrev_b32_e32 v96, 1, v142
	v_lshl_add_u64 v[130:131], v[130:131], 0, v[96:97]
	v_cvt_pk_bf16_f32 v132, v173, v205
	v_cvt_pk_bf16_f32 v133, v204, v206
	global_store_dwordx2 v[130:131], v[132:133], off offset:-1024
	s_ashr_i32 s93, s0, 31
	s_mov_b32 s92, s0
	v_lshlrev_b32_e32 v130, 2, v142
	v_lshlrev_b32_e32 v96, 2, v203
	v_mov_b32_e32 v96, v122
	v_mov_b32_e32 v131, v122
	s_nop 1
	v_permlane16_swap_b32_e32 v96, v131
	v_cndmask_b32_e64 v96, v96, v131, s[6:7]
	v_cndmask_b32_e64 v147, v96, -v96, s[10:11]
	v_mov_b32_e32 v148, v122
	v_mov_b32_e32 v131, v123
	s_waitcnt vmcnt(1)
	v_mov_b32_e32 v146, v216
	v_mov_b32_e32 v149, v220
	v_pk_mul_f32 v[146:147], v[148:149], v[146:147]
	v_mov_b32_e32 v186, v123
	v_add_f32_e32 v96, v146, v147
	v_cndmask_b32_e64 v126, v122, v96, s[8:9]
	v_mov_b32_e32 v96, v123
	s_nop 1
	v_permlane16_swap_b32_e32 v96, v131
	v_cndmask_b32_e64 v96, v96, v131, s[6:7]
	v_cndmask_b32_e64 v147, v96, -v96, s[10:11]
	v_mov_b32_e32 v146, v217
	v_mov_b32_e32 v187, v221
	v_pk_mul_f32 v[146:147], v[186:187], v[146:147]
	v_mov_b32_e32 v131, v124
	v_add_f32_e32 v96, v146, v147
	v_cndmask_b32_e64 v127, v123, v96, s[8:9]
	v_mov_b32_e32 v96, v124
	s_nop 1
	v_permlane16_swap_b32_e32 v96, v131
	v_cndmask_b32_e64 v96, v96, v131, s[6:7]
	v_cndmask_b32_e64 v147, v96, -v96, s[10:11]
	v_mov_b32_e32 v148, v124
	v_mov_b32_e32 v149, v222
	v_mov_b32_e32 v146, v218
	v_pk_mul_f32 v[146:147], v[148:149], v[146:147]
	v_mov_b32_e32 v131, v125
	v_add_f32_e32 v96, v146, v147
	v_cndmask_b32_e64 v128, v124, v96, s[8:9]
	v_mov_b32_e32 v96, v125
	s_nop 1
	v_permlane16_swap_b32_e32 v96, v131
	v_cndmask_b32_e64 v96, v96, v131, s[6:7]
	v_cndmask_b32_e64 v147, v96, -v96, s[10:11]
	v_mov_b32_e32 v188, v125
	v_mov_b32_e32 v146, v219
	v_mov_b32_e32 v189, v223
	v_pk_mul_f32 v[146:147], v[188:189], v[146:147]
	v_mov_b32_e32 v131, v126
	v_add_f32_e32 v96, v146, v147
	v_cndmask_b32_e64 v129, v125, v96, s[8:9]
	v_mov_b32_e32 v204, v127
	v_mov_b32_e32 v173, v128
	v_mov_b32_e32 v205, v129
	v_lshl_add_u64 v[126:127], s[82:83], 0, v[174:175]
	v_lshl_add_u64 v[126:127], s[0:1], 1, v[126:127]
	v_lshlrev_b32_e32 v96, 1, v142
	v_lshl_add_u64 v[126:127], v[126:127], 0, v[96:97]
	v_cvt_pk_bf16_f32 v128, v131, v204
	v_cvt_pk_bf16_f32 v129, v173, v205
	global_store_dwordx2 v[126:127], v[128:129], off offset:-1016
	v_readlane_b32 s70, v254, 59
	v_readlane_b32 s71, v254, 60
	v_lshlrev_b32_e32 v96, 2, v203
	v_mov_b32_e32 v96, v118
	v_mov_b32_e32 v128, v118
	s_nop 1
	v_permlane16_swap_b32_e32 v96, v128
	v_cndmask_b32_e64 v96, v96, v128, s[6:7]
	v_cndmask_b32_e64 v129, v96, -v96, s[10:11]
	v_mov_b32_e32 v146, v118
	v_mov_b32_e32 v128, v208
	v_mov_b32_e32 v147, v212
	v_pk_mul_f32 v[128:129], v[146:147], v[128:129]
	v_mov_b32_e32 v182, v119
	v_add_f32_e32 v96, v128, v129
	v_cndmask_b32_e64 v122, v118, v96, s[8:9]
	v_mov_b32_e32 v96, v119
	v_mov_b32_e32 v128, v119
	s_nop 1
	v_permlane16_swap_b32_e32 v96, v128
	v_cndmask_b32_e64 v96, v96, v128, s[6:7]
	v_cndmask_b32_e64 v129, v96, -v96, s[10:11]
	v_mov_b32_e32 v128, v209
	v_mov_b32_e32 v183, v213
	v_pk_mul_f32 v[128:129], v[182:183], v[128:129]
	v_mov_b32_e32 v146, v120
	v_add_f32_e32 v96, v128, v129
	v_cndmask_b32_e64 v123, v119, v96, s[8:9]
	v_mov_b32_e32 v96, v120
	v_mov_b32_e32 v128, v120
	s_nop 1
	v_permlane16_swap_b32_e32 v96, v128
	v_cndmask_b32_e64 v96, v96, v128, s[6:7]
	v_cndmask_b32_e64 v129, v96, -v96, s[10:11]
	v_mov_b32_e32 v147, v214
	v_mov_b32_e32 v128, v210
	v_pk_mul_f32 v[128:129], v[146:147], v[128:129]
	v_mov_b32_e32 v184, v121
	v_add_f32_e32 v96, v128, v129
	v_cndmask_b32_e64 v124, v120, v96, s[8:9]
	v_mov_b32_e32 v96, v121
; __device__ __forceinline__ float shx16(float v, int odd  ) { const unsigned x = __builtin_bit_cast(unsigned, v); auto r = __builtin_amdgcn_permlane16_swap(x, x, false, false); return __builtin_bit_cast(float, odd ? r[0] : r[1]); }
; __device__ __forceinline__ void st_bf4(bf16_t* p, const f32x4 v) { u32x2 w; w.x = cvt_pk_bf16(v[0], v[1]); w.y = cvt_pk_bf16(v[2], v[3]); *(u32x2*)p = w; }
;     __device__ __forceinline__ void operator()(const f32x4 (&acc)[2][2][4][2], const Unit& u, int wr, int wc, int fr, int fq) const {
;     ...
;                     for (int n = 0; n < 2; ++n) { const int tc = bj * 128 + wc * 32 + 8 * fq + 4 * n; f32x4 v = acc[ai][bj][m][n];
;                         if (pn < 2) { *(f32x4*)(XA + (size_t)row * 512 + pn * 256 + tc) = v; }
;                         else if (pn <= 4) {
;                             const bool isv = (pn == 4 && bj == 1);
;                             if (!isv && (wc & 1) == 0) {
;                                 const int tix = row < cfg::MP ? (row & 2047) : 2048 + (row & 3);
;                                 const f32x4 cs = *(const f32x4*)(ropec + tix * 8 + 4 * n), sn = *(const f32x4*)(ropes + tix * 8 + 4 * n);
; #pragma unroll
;                                 for (int i = 0; i < 4; ++i) { const float p = shx16(v[i], fq & 1); const float rv = v[i] * cs[i] + (fq == 0 ? -p : p) * sn[i]; v[i] = fq < 2 ? rv : v[i]; }
;                             }
;                             if (pn < 4) st_bf4(Q + (size_t)row * 512 + (pn - 2) * 256 + tc, v);
	v_mov_b32_e32 v128, v121
	s_nop 1
	v_permlane16_swap_b32_e32 v96, v128
	v_cndmask_b32_e64 v96, v96, v128, s[6:7]
	v_cndmask_b32_e64 v129, v96, -v96, s[10:11]
	v_mov_b32_e32 v128, v211
	v_mov_b32_e32 v185, v215
	v_pk_mul_f32 v[128:129], v[184:185], v[128:129]
	v_mov_b32_e32 v131, v122
	v_add_f32_e32 v96, v128, v129
	v_cndmask_b32_e64 v125, v121, v96, s[8:9]
	v_mov_b32_e32 v184, v123
	v_mov_b32_e32 v173, v124
	v_mov_b32_e32 v185, v125
	v_lshl_add_u64 v[122:123], s[82:83], 0, v[174:175]
	v_lshl_add_u64 v[122:123], s[0:1], 1, v[122:123]
	v_lshlrev_b32_e32 v96, 1, v142
	v_lshl_add_u64 v[122:123], v[122:123], 0, v[96:97]
	v_cvt_pk_bf16_f32 v124, v131, v184
	v_cvt_pk_bf16_f32 v125, v173, v185
	global_store_dwordx2 v[122:123], v[124:125], off offset:-768
	v_lshlrev_b32_e32 v96, 2, v203
	v_mov_b32_e32 v96, v114
	v_mov_b32_e32 v128, v114
	s_nop 1
	v_permlane16_swap_b32_e32 v96, v128
	v_cndmask_b32_e64 v96, v96, v128, s[6:7]
	v_cndmask_b32_e64 v129, v96, -v96, s[10:11]
	v_mov_b32_e32 v146, v114
	v_mov_b32_e32 v128, v216
	v_mov_b32_e32 v147, v220
	v_pk_mul_f32 v[128:129], v[146:147], v[128:129]
	v_mov_b32_e32 v122, v115
	v_add_f32_e32 v96, v128, v129
	v_cndmask_b32_e64 v118, v114, v96, s[8:9]
	v_mov_b32_e32 v96, v115
	s_nop 1
	v_permlane16_swap_b32_e32 v96, v122
	v_cndmask_b32_e64 v96, v96, v122, s[6:7]
	v_cndmask_b32_e64 v129, v96, -v96, s[10:11]
	v_mov_b32_e32 v122, v115
	v_mov_b32_e32 v128, v217
	v_mov_b32_e32 v123, v221
	v_pk_mul_f32 v[122:123], v[122:123], v[128:129]
	v_mov_b32_e32 v128, v116
	v_add_f32_e32 v96, v122, v123
	v_cndmask_b32_e64 v119, v115, v96, s[8:9]
	v_mov_b32_e32 v96, v116
	v_mov_b32_e32 v122, v116
	s_nop 1
	v_permlane16_swap_b32_e32 v96, v122
	v_cndmask_b32_e64 v96, v96, v122, s[6:7]
	v_cndmask_b32_e64 v123, v96, -v96, s[10:11]
	v_mov_b32_e32 v129, v222
	v_mov_b32_e32 v122, v218
	v_pk_mul_f32 v[122:123], v[128:129], v[122:123]
	v_mov_b32_e32 v124, v117
	v_add_f32_e32 v96, v122, v123
	v_cndmask_b32_e64 v120, v116, v96, s[8:9]
	v_mov_b32_e32 v96, v117
	v_mov_b32_e32 v122, v117
	s_nop 1
	v_permlane16_swap_b32_e32 v96, v122
	v_cndmask_b32_e64 v96, v96, v122, s[6:7]
	v_cndmask_b32_e64 v123, v96, -v96, s[10:11]
	v_mov_b32_e32 v122, v219
	v_mov_b32_e32 v125, v223
	v_pk_mul_f32 v[122:123], v[124:125], v[122:123]
	v_mov_b32_e32 v128, v118
	v_add_f32_e32 v96, v122, v123
	v_cndmask_b32_e64 v121, v117, v96, s[8:9]
	v_mov_b32_e32 v131, v119
	v_mov_b32_e32 v129, v120
	v_mov_b32_e32 v173, v121
	s_mov_b64 s[70:71], -1
	s_andn2_b64 vcc, exec, s[70:71]
	v_lshl_add_u64 v[118:119], s[82:83], 0, v[174:175]
	v_lshl_add_u64 v[118:119], s[0:1], 1, v[118:119]
	v_lshlrev_b32_e32 v96, 1, v142
	v_lshl_add_u64 v[118:119], v[118:119], 0, v[96:97]
	v_cvt_pk_bf16_f32 v120, v128, v131
	v_cvt_pk_bf16_f32 v121, v129, v173
	global_store_dwordx2 v[118:119], v[120:121], off offset:-760
	v_or_b32_e32 v114, 16, v172
	v_mad_i64_i32 v[124:125], s[18:19], v114, s61, 0
	s_movk_i32 s18, 0x7df
	s_nop 0
	v_bitop3_b32 v96, v172, s18, 16 bitop3:0xc8
	s_movk_i32 s18, 0x4000
	v_cmp_gt_i32_e32 vcc, s18, v114
	s_nop 1
	v_cndmask_b32_e32 v116, v151, v96, vcc
	v_ashrrev_i32_e32 v115, 31, v114
	v_lshlrev_b32_e32 v176, 3, v116
	v_add_u32_e32 v116, 0xffffc010, v172
	v_lshrrev_b32_e32 v173, 2, v116
	v_lshlrev_b64 v[118:119], 10, v[114:115]
	v_lshlrev_b32_e32 v96, 2, v176
	global_load_dwordx4 v[208:211], v96, s[44:45]
	global_load_dwordx4 v[212:215], v96, s[4:5]
	global_load_dwordx4 v[216:219], v96, s[44:45] offset:16
	global_load_dwordx4 v[220:223], v96, s[4:5] offset:16
	v_mov_b32_e32 v96, v110
	v_mov_b32_e32 v131, v110
	s_nop 1
	v_permlane16_swap_b32_e32 v96, v131
	v_cndmask_b32_e64 v96, v96, v131, s[6:7]
	v_cndmask_b32_e64 v133, v96, -v96, s[10:11]
	v_mov_b32_e32 v146, v110
	v_mov_b32_e32 v131, v111
	s_waitcnt vmcnt(2)
	v_mov_b32_e32 v132, v208
	v_mov_b32_e32 v147, v212
	v_pk_mul_f32 v[132:133], v[146:147], v[132:133]
	v_mov_b32_e32 v178, v111
	v_add_f32_e32 v96, v132, v133
	v_cndmask_b32_e64 v114, v110, v96, s[8:9]
	v_mov_b32_e32 v96, v111
	s_nop 1
	v_permlane16_swap_b32_e32 v96, v131
	v_cndmask_b32_e64 v96, v96, v131, s[6:7]
	v_cndmask_b32_e64 v133, v96, -v96, s[10:11]
	v_mov_b32_e32 v132, v209
	v_mov_b32_e32 v179, v213
	v_pk_mul_f32 v[132:133], v[178:179], v[132:133]
	v_mov_b32_e32 v131, v112
	v_add_f32_e32 v96, v132, v133
	v_cndmask_b32_e64 v115, v111, v96, s[8:9]
	v_mov_b32_e32 v96, v112
	s_nop 1
	v_permlane16_swap_b32_e32 v96, v131
	v_cndmask_b32_e64 v96, v96, v131, s[6:7]
	v_cndmask_b32_e64 v133, v96, -v96, s[10:11]
	v_mov_b32_e32 v146, v112
	v_mov_b32_e32 v147, v214
	v_mov_b32_e32 v132, v210
	v_pk_mul_f32 v[132:133], v[146:147], v[132:133]
	v_mov_b32_e32 v131, v113
	v_add_f32_e32 v96, v132, v133
	v_cndmask_b32_e64 v116, v112, v96, s[8:9]
	v_mov_b32_e32 v96, v113
	s_nop 1
	v_permlane16_swap_b32_e32 v96, v131
	v_cndmask_b32_e64 v96, v96, v131, s[6:7]
	v_cndmask_b32_e64 v133, v96, -v96, s[10:11]
	v_mov_b32_e32 v180, v113
	v_mov_b32_e32 v132, v211
	v_mov_b32_e32 v181, v215
	v_pk_mul_f32 v[132:133], v[180:181], v[132:133]
	v_mov_b32_e32 v131, v114
	v_add_f32_e32 v96, v132, v133
	v_cndmask_b32_e64 v117, v113, v96, s[8:9]
	v_mov_b32_e32 v178, v115
	v_mov_b32_e32 v177, v116
	v_mov_b32_e32 v179, v117
	v_lshl_add_u64 v[114:115], s[82:83], 0, v[118:119]
	v_lshl_add_u64 v[114:115], s[0:1], 1, v[114:115]
	v_lshlrev_b32_e32 v96, 1, v142
	v_lshl_add_u64 v[114:115], v[114:115], 0, v[96:97]
	v_cvt_pk_bf16_f32 v116, v131, v178
	v_cvt_pk_bf16_f32 v117, v177, v179
	global_store_dwordx2 v[114:115], v[116:117], off offset:-1024
	v_lshlrev_b32_e32 v96, 2, v176
	v_mov_b32_e32 v96, v106
	v_mov_b32_e32 v116, v106
	s_nop 1
	v_permlane16_swap_b32_e32 v96, v116
	v_cndmask_b32_e64 v96, v96, v116, s[6:7]
	v_cndmask_b32_e64 v117, v96, -v96, s[10:11]
	v_mov_b32_e32 v132, v106
	s_waitcnt vmcnt(1)
; __device__ __forceinline__ float shx16(float v, int odd  ) { const unsigned x = __builtin_bit_cast(unsigned, v); auto r = __builtin_amdgcn_permlane16_swap(x, x, false, false); return __builtin_bit_cast(float, odd ? r[0] : r[1]); }
; __device__ __forceinline__ void st_bf4(bf16_t* p, const f32x4 v) { u32x2 w; w.x = cvt_pk_bf16(v[0], v[1]); w.y = cvt_pk_bf16(v[2], v[3]); *(u32x2*)p = w; }
;     __device__ __forceinline__ void operator()(const f32x4 (&acc)[2][2][4][2], const Unit& u, int wr, int wc, int fr, int fq) const {
;     ...
;                     for (int n = 0; n < 2; ++n) { const int tc = bj * 128 + wc * 32 + 8 * fq + 4 * n; f32x4 v = acc[ai][bj][m][n];
;                         if (pn < 2) { *(f32x4*)(XA + (size_t)row * 512 + pn * 256 + tc) = v; }
;                         else if (pn <= 4) {
;                             const bool isv = (pn == 4 && bj == 1);
;                             if (!isv && (wc & 1) == 0) {
;                                 const int tix = row < cfg::MP ? (row & 2047) : 2048 + (row & 3);
;                                 const f32x4 cs = *(const f32x4*)(ropec + tix * 8 + 4 * n), sn = *(const f32x4*)(ropes + tix * 8 + 4 * n);
; #pragma unroll
;                                 for (int i = 0; i < 4; ++i) { const float p = shx16(v[i], fq & 1); const float rv = v[i] * cs[i] + (fq == 0 ? -p : p) * sn[i]; v[i] = fq < 2 ? rv : v[i]; }
;                             }
;                             if (pn < 4) st_bf4(Q + (size_t)row * 512 + (pn - 2) * 256 + tc, v);
	v_mov_b32_e32 v116, v216
	v_mov_b32_e32 v133, v220
	v_pk_mul_f32 v[116:117], v[132:133], v[116:117]
	v_mov_b32_e32 v178, v107
	v_add_f32_e32 v96, v116, v117
	v_cndmask_b32_e64 v110, v106, v96, s[8:9]
	v_mov_b32_e32 v96, v107
	v_mov_b32_e32 v116, v107
	s_nop 1
	v_permlane16_swap_b32_e32 v96, v116
	v_cndmask_b32_e64 v96, v96, v116, s[6:7]
	v_cndmask_b32_e64 v117, v96, -v96, s[10:11]
	v_mov_b32_e32 v116, v217
	v_mov_b32_e32 v179, v221
	v_pk_mul_f32 v[116:117], v[178:179], v[116:117]
	v_mov_b32_e32 v132, v108
	v_add_f32_e32 v96, v116, v117
	v_cndmask_b32_e64 v111, v107, v96, s[8:9]
	v_mov_b32_e32 v96, v108
	v_mov_b32_e32 v116, v108
	s_nop 1
	v_permlane16_swap_b32_e32 v96, v116
	v_cndmask_b32_e64 v96, v96, v116, s[6:7]
	v_cndmask_b32_e64 v117, v96, -v96, s[10:11]
	v_mov_b32_e32 v133, v222
	v_mov_b32_e32 v116, v218
	v_pk_mul_f32 v[116:117], v[132:133], v[116:117]
	v_mov_b32_e32 v180, v109
	v_add_f32_e32 v96, v116, v117
	v_cndmask_b32_e64 v112, v108, v96, s[8:9]
	v_mov_b32_e32 v96, v109
	v_mov_b32_e32 v116, v109
	s_nop 1
	v_permlane16_swap_b32_e32 v96, v116
	v_cndmask_b32_e64 v96, v96, v116, s[6:7]
	v_cndmask_b32_e64 v117, v96, -v96, s[10:11]
	v_mov_b32_e32 v116, v219
	v_mov_b32_e32 v181, v223
	v_pk_mul_f32 v[116:117], v[180:181], v[116:117]
	v_mov_b32_e32 v131, v110
	v_add_f32_e32 v96, v116, v117
	v_cndmask_b32_e64 v113, v109, v96, s[8:9]
	v_mov_b32_e32 v175, v111
	v_mov_b32_e32 v174, v112
	v_mov_b32_e32 v177, v113
	v_lshl_add_u64 v[110:111], s[82:83], 0, v[118:119]
	v_lshl_add_u64 v[110:111], s[0:1], 1, v[110:111]
	v_lshlrev_b32_e32 v96, 1, v142
	v_lshl_add_u64 v[110:111], v[110:111], 0, v[96:97]
	v_cvt_pk_bf16_f32 v112, v131, v175
	v_cvt_pk_bf16_f32 v113, v174, v177
	global_store_dwordx2 v[110:111], v[112:113], off offset:-1016
	v_lshlrev_b32_e32 v96, 2, v176
	v_mov_b32_e32 v96, v102
	v_mov_b32_e32 v112, v102
	s_nop 1
	v_permlane16_swap_b32_e32 v96, v112
	v_cndmask_b32_e64 v96, v96, v112, s[6:7]
	v_cndmask_b32_e64 v113, v96, -v96, s[10:11]
	v_mov_b32_e32 v116, v102
	v_mov_b32_e32 v112, v208
	v_mov_b32_e32 v117, v212
	v_pk_mul_f32 v[112:113], v[116:117], v[112:113]
	v_mov_b32_e32 v126, v103
	v_add_f32_e32 v96, v112, v113
	v_cndmask_b32_e64 v106, v102, v96, s[8:9]
	v_mov_b32_e32 v96, v103
	v_mov_b32_e32 v112, v103
	s_nop 1
	v_permlane16_swap_b32_e32 v96, v112
	v_cndmask_b32_e64 v96, v96, v112, s[6:7]
	v_cndmask_b32_e64 v113, v96, -v96, s[10:11]
	v_mov_b32_e32 v112, v209
	v_mov_b32_e32 v127, v213
	v_pk_mul_f32 v[112:113], v[126:127], v[112:113]
	v_mov_b32_e32 v116, v104
	v_add_f32_e32 v96, v112, v113
	v_cndmask_b32_e64 v107, v103, v96, s[8:9]
	v_mov_b32_e32 v96, v104
	v_mov_b32_e32 v112, v104
	s_nop 1
	v_permlane16_swap_b32_e32 v96, v112
	v_cndmask_b32_e64 v96, v96, v112, s[6:7]
	v_cndmask_b32_e64 v113, v96, -v96, s[10:11]
	v_mov_b32_e32 v117, v214
	v_mov_b32_e32 v112, v210
	v_pk_mul_f32 v[112:113], v[116:117], v[112:113]
	v_mov_b32_e32 v128, v105
	v_add_f32_e32 v96, v112, v113
	v_cndmask_b32_e64 v108, v104, v96, s[8:9]
	v_mov_b32_e32 v96, v105
	v_mov_b32_e32 v112, v105
	s_nop 1
	v_permlane16_swap_b32_e32 v96, v112
	v_cndmask_b32_e64 v96, v96, v112, s[6:7]
	v_cndmask_b32_e64 v113, v96, -v96, s[10:11]
	v_mov_b32_e32 v112, v211
	v_mov_b32_e32 v129, v215
	v_pk_mul_f32 v[112:113], v[128:129], v[112:113]
	v_mov_b32_e32 v126, v106
	v_add_f32_e32 v96, v112, v113
	v_cndmask_b32_e64 v109, v105, v96, s[8:9]
	v_mov_b32_e32 v128, v107
	v_mov_b32_e32 v127, v108
	v_mov_b32_e32 v129, v109
	v_lshl_add_u64 v[106:107], s[82:83], 0, v[118:119]
	v_lshl_add_u64 v[106:107], s[0:1], 1, v[106:107]
	v_lshlrev_b32_e32 v96, 1, v142
	v_lshl_add_u64 v[106:107], v[106:107], 0, v[96:97]
	v_cvt_pk_bf16_f32 v108, v126, v128
	v_cvt_pk_bf16_f32 v109, v127, v129
	global_store_dwordx2 v[106:107], v[108:109], off offset:-768
	v_lshlrev_b32_e32 v96, 2, v176
	v_mov_b32_e32 v96, v98
	v_mov_b32_e32 v112, v98
	s_nop 1
	v_permlane16_swap_b32_e32 v96, v112
	v_cndmask_b32_e64 v96, v96, v112, s[6:7]
	v_cndmask_b32_e64 v113, v96, -v96, s[10:11]
	v_mov_b32_e32 v116, v98
	v_mov_b32_e32 v112, v216
	v_mov_b32_e32 v117, v220
	v_pk_mul_f32 v[112:113], v[116:117], v[112:113]
	v_mov_b32_e32 v106, v99
	v_add_f32_e32 v96, v112, v113
	v_cndmask_b32_e64 v102, v98, v96, s[8:9]
	v_mov_b32_e32 v96, v99
	s_nop 1
	v_permlane16_swap_b32_e32 v96, v106
	v_cndmask_b32_e64 v96, v96, v106, s[6:7]
	v_cndmask_b32_e64 v113, v96, -v96, s[10:11]
	v_mov_b32_e32 v106, v99
	v_mov_b32_e32 v112, v217
	v_mov_b32_e32 v107, v221
	v_pk_mul_f32 v[106:107], v[106:107], v[112:113]
	v_mov_b32_e32 v112, v100
	v_add_f32_e32 v96, v106, v107
	v_cndmask_b32_e64 v103, v99, v96, s[8:9]
	v_mov_b32_e32 v96, v100
	v_mov_b32_e32 v106, v100
	s_nop 1
	v_permlane16_swap_b32_e32 v96, v106
	v_cndmask_b32_e64 v96, v96, v106, s[6:7]
	v_cndmask_b32_e64 v107, v96, -v96, s[10:11]
	v_mov_b32_e32 v113, v222
	v_mov_b32_e32 v106, v218
	v_pk_mul_f32 v[106:107], v[112:113], v[106:107]
	v_mov_b32_e32 v108, v101
	v_add_f32_e32 v96, v106, v107
	v_cndmask_b32_e64 v104, v100, v96, s[8:9]
	v_mov_b32_e32 v96, v101
	v_mov_b32_e32 v106, v101
	s_nop 1
	v_permlane16_swap_b32_e32 v96, v106
	v_cndmask_b32_e64 v96, v96, v106, s[6:7]
	v_cndmask_b32_e64 v107, v96, -v96, s[10:11]
	v_mov_b32_e32 v106, v219
	v_mov_b32_e32 v109, v223
	v_pk_mul_f32 v[106:107], v[108:109], v[106:107]
	v_mov_b32_e32 v112, v102
	v_add_f32_e32 v96, v106, v107
	v_cndmask_b32_e64 v105, v101, v96, s[8:9]
	v_mov_b32_e32 v116, v103
	v_mov_b32_e32 v113, v104
	v_mov_b32_e32 v117, v105
	s_mov_b64 s[70:71], -1
	s_andn2_b64 vcc, exec, s[70:71]
	v_lshl_add_u64 v[102:103], s[82:83], 0, v[118:119]
	v_lshl_add_u64 v[102:103], s[0:1], 1, v[102:103]
	v_lshlrev_b32_e32 v96, 1, v142
	v_lshl_add_u64 v[102:103], v[102:103], 0, v[96:97]
	v_cvt_pk_bf16_f32 v104, v112, v116
	v_cvt_pk_bf16_f32 v105, v113, v117
	global_store_dwordx2 v[102:103], v[104:105], off offset:-760
	v_or_b32_e32 v98, 32, v172
	v_mad_i64_i32 v[108:109], s[18:19], v98, s61, 0
	s_movk_i32 s18, 0x7ef
	s_nop 0
	v_bitop3_b32 v96, v172, s18, 32 bitop3:0xc8
	s_movk_i32 s18, 0x4000
	v_cmp_gt_i32_e32 vcc, s18, v98
	s_nop 1
	v_cndmask_b32_e32 v100, v151, v96, vcc
	v_ashrrev_i32_e32 v99, 31, v98
	v_lshlrev_b32_e32 v119, 3, v100
	v_add_u32_e32 v100, 0xffffc020, v172
	v_lshrrev_b32_e32 v118, 2, v100
	v_lshlrev_b64 v[102:103], 10, v[98:99]
	v_lshlrev_b32_e32 v96, 2, v119
	global_load_dwordx4 v[208:211], v96, s[44:45]
	global_load_dwordx4 v[212:215], v96, s[4:5]
	global_load_dwordx4 v[216:219], v96, s[44:45] offset:16
	global_load_dwordx4 v[220:223], v96, s[4:5] offset:16
	v_mov_b32_e32 v96, v92
	v_mov_b32_e32 v120, v92
	s_nop 1
	v_permlane16_swap_b32_e32 v96, v120
	v_cndmask_b32_e64 v96, v96, v120, s[6:7]
	v_cndmask_b32_e64 v121, v96, -v96, s[10:11]
	v_mov_b32_e32 v122, v92
	s_waitcnt vmcnt(2)
; __device__ __forceinline__ float shx16(float v, int odd  ) { const unsigned x = __builtin_bit_cast(unsigned, v); auto r = __builtin_amdgcn_permlane16_swap(x, x, false, false); return __builtin_bit_cast(float, odd ? r[0] : r[1]); }
; __device__ __forceinline__ void st_bf4(bf16_t* p, const f32x4 v) { u32x2 w; w.x = cvt_pk_bf16(v[0], v[1]); w.y = cvt_pk_bf16(v[2], v[3]); *(u32x2*)p = w; }
;     __device__ __forceinline__ void operator()(const f32x4 (&acc)[2][2][4][2], const Unit& u, int wr, int wc, int fr, int fq) const {
;     ...
;                     for (int n = 0; n < 2; ++n) { const int tc = bj * 128 + wc * 32 + 8 * fq + 4 * n; f32x4 v = acc[ai][bj][m][n];
;                         if (pn < 2) { *(f32x4*)(XA + (size_t)row * 512 + pn * 256 + tc) = v; }
;                         else if (pn <= 4) {
;                             const bool isv = (pn == 4 && bj == 1);
;                             if (!isv && (wc & 1) == 0) {
;                                 const int tix = row < cfg::MP ? (row & 2047) : 2048 + (row & 3);
;                                 const f32x4 cs = *(const f32x4*)(ropec + tix * 8 + 4 * n), sn = *(const f32x4*)(ropes + tix * 8 + 4 * n);
; #pragma unroll
;                                 for (int i = 0; i < 4; ++i) { const float p = shx16(v[i], fq & 1); const float rv = v[i] * cs[i] + (fq == 0 ? -p : p) * sn[i]; v[i] = fq < 2 ? rv : v[i]; }
;                             }
;                             if (pn < 4) st_bf4(Q + (size_t)row * 512 + (pn - 2) * 256 + tc, v);
	v_mov_b32_e32 v120, v208
	v_mov_b32_e32 v123, v212
	v_pk_mul_f32 v[120:121], v[122:123], v[120:121]
	v_mov_b32_e32 v114, v93
	v_add_f32_e32 v96, v120, v121
	v_cndmask_b32_e64 v98, v92, v96, s[8:9]
	v_mov_b32_e32 v96, v93
	s_nop 1
	v_permlane16_swap_b32_e32 v96, v114
	v_cndmask_b32_e64 v96, v96, v114, s[6:7]
	v_cndmask_b32_e64 v121, v96, -v96, s[10:11]
	v_mov_b32_e32 v114, v93
	v_mov_b32_e32 v120, v209
	v_mov_b32_e32 v115, v213
	v_pk_mul_f32 v[114:115], v[114:115], v[120:121]
	v_mov_b32_e32 v120, v94
	v_add_f32_e32 v96, v114, v115
	v_cndmask_b32_e64 v99, v93, v96, s[8:9]
	v_mov_b32_e32 v96, v94
	v_mov_b32_e32 v114, v94
	s_nop 1
	v_permlane16_swap_b32_e32 v96, v114
	v_cndmask_b32_e64 v96, v96, v114, s[6:7]
	v_cndmask_b32_e64 v115, v96, -v96, s[10:11]
	v_mov_b32_e32 v121, v214
	v_mov_b32_e32 v114, v210
	v_pk_mul_f32 v[114:115], v[120:121], v[114:115]
	v_mov_b32_e32 v116, v95
	v_add_f32_e32 v96, v114, v115
	v_cndmask_b32_e64 v100, v94, v96, s[8:9]
	v_mov_b32_e32 v96, v95
	v_mov_b32_e32 v114, v95
	s_nop 1
	v_permlane16_swap_b32_e32 v96, v114
	v_cndmask_b32_e64 v96, v96, v114, s[6:7]
	v_cndmask_b32_e64 v115, v96, -v96, s[10:11]
	v_mov_b32_e32 v114, v211
	v_mov_b32_e32 v117, v215
	v_pk_mul_f32 v[114:115], v[116:117], v[114:115]
	v_mov_b32_e32 v120, v98
	v_add_f32_e32 v96, v114, v115
	v_cndmask_b32_e64 v101, v95, v96, s[8:9]
	v_mov_b32_e32 v122, v99
	v_mov_b32_e32 v121, v100
	v_mov_b32_e32 v123, v101
	v_lshl_add_u64 v[98:99], s[82:83], 0, v[102:103]
	v_lshl_add_u64 v[98:99], s[0:1], 1, v[98:99]
	v_lshlrev_b32_e32 v96, 1, v142
	v_lshl_add_u64 v[98:99], v[98:99], 0, v[96:97]
	v_cvt_pk_bf16_f32 v100, v120, v122
	v_cvt_pk_bf16_f32 v101, v121, v123
	global_store_dwordx2 v[98:99], v[100:101], off offset:-1024
	v_lshlrev_b32_e32 v96, 2, v119
	v_mov_b32_e32 v96, v88
	v_mov_b32_e32 v100, v88
	s_nop 1
	v_permlane16_swap_b32_e32 v96, v100
	v_cndmask_b32_e64 v96, v96, v100, s[6:7]
	v_cndmask_b32_e64 v101, v96, -v96, s[10:11]
	v_mov_b32_e32 v120, v88
	v_mov_b32_e32 v96, v89
	s_waitcnt vmcnt(1)
	v_mov_b32_e32 v100, v216
	v_mov_b32_e32 v121, v220
	v_pk_mul_f32 v[100:101], v[120:121], v[100:101]
	v_mov_b32_e32 v114, v89
	v_add_f32_e32 v92, v100, v101
	v_mov_b32_e32 v100, v89
	s_nop 1
	v_permlane16_swap_b32_e32 v96, v100
	v_cndmask_b32_e64 v96, v96, v100, s[6:7]
	v_cndmask_b32_e64 v101, v96, -v96, s[10:11]
	v_mov_b32_e32 v100, v217
	v_mov_b32_e32 v115, v221
	v_pk_mul_f32 v[100:101], v[114:115], v[100:101]
	v_mov_b32_e32 v96, v90
	v_add_f32_e32 v93, v100, v101
	v_mov_b32_e32 v100, v90
	s_nop 1
	v_permlane16_swap_b32_e32 v96, v100
	v_cndmask_b32_e64 v96, v96, v100, s[6:7]
	v_cndmask_b32_e64 v101, v96, -v96, s[10:11]
	v_mov_b32_e32 v114, v90
	v_mov_b32_e32 v115, v222
	v_mov_b32_e32 v100, v218
	v_pk_mul_f32 v[100:101], v[114:115], v[100:101]
	v_mov_b32_e32 v96, v91
	v_add_f32_e32 v94, v100, v101
	v_mov_b32_e32 v100, v91
	s_nop 1
	v_permlane16_swap_b32_e32 v96, v100
	v_cndmask_b32_e64 v96, v96, v100, s[6:7]
	v_cndmask_b32_e64 v101, v96, -v96, s[10:11]
	v_mov_b32_e32 v116, v91
	v_mov_b32_e32 v100, v219
	v_mov_b32_e32 v117, v223
	v_pk_mul_f32 v[100:101], v[116:117], v[100:101]
	v_cndmask_b32_e64 v92, v88, v92, s[8:9]
	v_add_f32_e32 v95, v100, v101
	v_cndmask_b32_e64 v93, v89, v93, s[8:9]
	v_cndmask_b32_e64 v94, v90, v94, s[8:9]
	v_cndmask_b32_e64 v95, v91, v95, s[8:9]
	v_mov_b32_e32 v116, v92
	v_mov_b32_e32 v120, v93
	v_mov_b32_e32 v117, v94
	v_mov_b32_e32 v121, v95
	v_lshl_add_u64 v[92:93], s[82:83], 0, v[102:103]
	v_lshl_add_u64 v[92:93], s[0:1], 1, v[92:93]
	v_lshlrev_b32_e32 v96, 1, v142
	v_lshl_add_u64 v[92:93], v[92:93], 0, v[96:97]
	v_cvt_pk_bf16_f32 v94, v116, v120
	v_cvt_pk_bf16_f32 v95, v117, v121
	global_store_dwordx2 v[92:93], v[94:95], off offset:-1016
	v_lshlrev_b32_e32 v94, 2, v119
	v_mov_b32_e32 v94, v84
	v_mov_b32_e32 v95, v84
	s_nop 1
	v_permlane16_swap_b32_e32 v94, v95
	v_cndmask_b32_e64 v94, v94, v95, s[6:7]
	v_cndmask_b32_e64 v95, v94, -v94, s[10:11]
	v_mov_b32_e32 v100, v84
	v_mov_b32_e32 v94, v208
	v_mov_b32_e32 v101, v212
	v_pk_mul_f32 v[94:95], v[100:101], v[94:95]
	v_mov_b32_e32 v110, v85
	v_add_f32_e32 v88, v94, v95
	v_mov_b32_e32 v94, v85
	v_mov_b32_e32 v95, v85
	s_nop 1
	v_permlane16_swap_b32_e32 v94, v95
	v_cndmask_b32_e64 v94, v94, v95, s[6:7]
	v_cndmask_b32_e64 v95, v94, -v94, s[10:11]
	v_mov_b32_e32 v94, v209
	v_mov_b32_e32 v111, v213
	v_pk_mul_f32 v[94:95], v[110:111], v[94:95]
	v_mov_b32_e32 v100, v86
	v_add_f32_e32 v89, v94, v95
	v_mov_b32_e32 v94, v86
	v_mov_b32_e32 v95, v86
	s_nop 1
	v_permlane16_swap_b32_e32 v94, v95
	v_cndmask_b32_e64 v94, v94, v95, s[6:7]
	v_cndmask_b32_e64 v95, v94, -v94, s[10:11]
	v_mov_b32_e32 v101, v214
	v_mov_b32_e32 v94, v210
	v_pk_mul_f32 v[94:95], v[100:101], v[94:95]
	v_mov_b32_e32 v112, v87
	v_add_f32_e32 v90, v94, v95
	v_mov_b32_e32 v94, v87
	v_mov_b32_e32 v95, v87
	s_nop 1
	v_permlane16_swap_b32_e32 v94, v95
	v_cndmask_b32_e64 v94, v94, v95, s[6:7]
	v_cndmask_b32_e64 v95, v94, -v94, s[10:11]
	v_mov_b32_e32 v94, v211
	v_mov_b32_e32 v113, v215
	v_pk_mul_f32 v[94:95], v[112:113], v[94:95]
	v_cndmask_b32_e64 v88, v84, v88, s[8:9]
	v_add_f32_e32 v91, v94, v95
	v_cndmask_b32_e64 v89, v85, v89, s[8:9]
	v_cndmask_b32_e64 v90, v86, v90, s[8:9]
	v_cndmask_b32_e64 v91, v87, v91, s[8:9]
	v_mov_b32_e32 v110, v88
	v_mov_b32_e32 v112, v89
	v_mov_b32_e32 v111, v90
	v_mov_b32_e32 v113, v91
	v_lshl_add_u64 v[88:89], s[82:83], 0, v[102:103]
	v_lshl_add_u64 v[88:89], s[0:1], 1, v[88:89]
	v_lshlrev_b32_e32 v96, 1, v142
	v_lshl_add_u64 v[88:89], v[88:89], 0, v[96:97]
	v_cvt_pk_bf16_f32 v90, v110, v112
	v_cvt_pk_bf16_f32 v91, v111, v113
	global_store_dwordx2 v[88:89], v[90:91], off offset:-768
	v_lshlrev_b32_e32 v88, 2, v119
; __device__ __forceinline__ float shx16(float v, int odd  ) { const unsigned x = __builtin_bit_cast(unsigned, v); auto r = __builtin_amdgcn_permlane16_swap(x, x, false, false); return __builtin_bit_cast(float, odd ? r[0] : r[1]); }
; __device__ __forceinline__ void st_bf4(bf16_t* p, const f32x4 v) { u32x2 w; w.x = cvt_pk_bf16(v[0], v[1]); w.y = cvt_pk_bf16(v[2], v[3]); *(u32x2*)p = w; }
;     __device__ __forceinline__ void operator()(const f32x4 (&acc)[2][2][4][2], const Unit& u, int wr, int wc, int fr, int fq) const {
;     ...
;                     for (int n = 0; n < 2; ++n) { const int tc = bj * 128 + wc * 32 + 8 * fq + 4 * n; f32x4 v = acc[ai][bj][m][n];
;                         if (pn < 2) { *(f32x4*)(XA + (size_t)row * 512 + pn * 256 + tc) = v; }
;                         else if (pn <= 4) {
;                             const bool isv = (pn == 4 && bj == 1);
;                             if (!isv && (wc & 1) == 0) {
;                                 const int tix = row < cfg::MP ? (row & 2047) : 2048 + (row & 3);
;                                 const f32x4 cs = *(const f32x4*)(ropec + tix * 8 + 4 * n), sn = *(const f32x4*)(ropes + tix * 8 + 4 * n);
; #pragma unroll
;                                 for (int i = 0; i < 4; ++i) { const float p = shx16(v[i], fq & 1); const float rv = v[i] * cs[i] + (fq == 0 ? -p : p) * sn[i]; v[i] = fq < 2 ? rv : v[i]; }
;                             }
;                             if (pn < 4) st_bf4(Q + (size_t)row * 512 + (pn - 2) * 256 + tc, v);
	v_mov_b32_e32 v94, v80
	v_mov_b32_e32 v95, v80
	s_nop 1
	v_permlane16_swap_b32_e32 v94, v95
	v_cndmask_b32_e64 v94, v94, v95, s[6:7]
	v_cndmask_b32_e64 v95, v94, -v94, s[10:11]
	v_mov_b32_e32 v100, v80
	v_mov_b32_e32 v94, v216
	v_mov_b32_e32 v101, v220
	v_pk_mul_f32 v[94:95], v[100:101], v[94:95]
	v_mov_b32_e32 v88, v81
	v_add_f32_e32 v84, v94, v95
	v_mov_b32_e32 v94, v81
	s_nop 1
	v_permlane16_swap_b32_e32 v88, v94
	v_cndmask_b32_e64 v88, v88, v94, s[6:7]
	v_cndmask_b32_e64 v95, v88, -v88, s[10:11]
	v_mov_b32_e32 v88, v81
	v_mov_b32_e32 v94, v217
	v_mov_b32_e32 v89, v221
	v_pk_mul_f32 v[88:89], v[88:89], v[94:95]
	v_mov_b32_e32 v94, v82
	v_add_f32_e32 v85, v88, v89
	v_mov_b32_e32 v88, v82
	v_mov_b32_e32 v89, v82
	s_nop 1
	v_permlane16_swap_b32_e32 v88, v89
	v_cndmask_b32_e64 v88, v88, v89, s[6:7]
	v_cndmask_b32_e64 v89, v88, -v88, s[10:11]
	v_mov_b32_e32 v95, v222
	v_mov_b32_e32 v88, v218
	v_pk_mul_f32 v[88:89], v[94:95], v[88:89]
	v_mov_b32_e32 v90, v83
	v_add_f32_e32 v86, v88, v89
	v_mov_b32_e32 v88, v83
	v_mov_b32_e32 v89, v83
	s_nop 1
	v_permlane16_swap_b32_e32 v88, v89
	v_cndmask_b32_e64 v88, v88, v89, s[6:7]
	v_cndmask_b32_e64 v89, v88, -v88, s[10:11]
	v_mov_b32_e32 v88, v219
	v_mov_b32_e32 v91, v223
	v_pk_mul_f32 v[88:89], v[90:91], v[88:89]
	v_cndmask_b32_e64 v84, v80, v84, s[8:9]
	v_add_f32_e32 v87, v88, v89
	v_cndmask_b32_e64 v85, v81, v85, s[8:9]
	v_cndmask_b32_e64 v86, v82, v86, s[8:9]
	v_cndmask_b32_e64 v87, v83, v87, s[8:9]
	v_mov_b32_e32 v94, v84
	v_mov_b32_e32 v100, v85
	v_mov_b32_e32 v95, v86
	v_mov_b32_e32 v101, v87
	s_mov_b64 s[70:71], -1
	s_andn2_b64 vcc, exec, s[70:71]
	v_lshl_add_u64 v[84:85], s[82:83], 0, v[102:103]
	v_lshl_add_u64 v[84:85], s[0:1], 1, v[84:85]
	v_lshlrev_b32_e32 v96, 1, v142
	v_lshl_add_u64 v[84:85], v[84:85], 0, v[96:97]
	v_cvt_pk_bf16_f32 v86, v94, v100
	v_cvt_pk_bf16_f32 v87, v95, v101
	global_store_dwordx2 v[84:85], v[86:87], off offset:-760
	v_or_b32_e32 v80, 48, v172
	s_movk_i32 s18, 0x7ff
	v_bitop3_b32 v82, v172, s18, 48 bitop3:0xc8
	s_movk_i32 s18, 0x4000
	v_cmp_gt_i32_e32 vcc, s18, v80
	v_ashrrev_i32_e32 v81, 31, v80
	s_nop 0
	v_cndmask_b32_e32 v83, v151, v82, vcc
	v_lshlrev_b32_e32 v103, 3, v83
	v_add_u32_e32 v83, 0xffffc030, v172
	v_lshrrev_b32_e32 v102, 2, v83
	v_lshlrev_b64 v[84:85], 10, v[80:81]
	v_lshlrev_b32_e32 v96, 2, v103
	global_load_dwordx4 v[208:211], v96, s[44:45]
	global_load_dwordx4 v[212:215], v96, s[4:5]
	global_load_dwordx4 v[216:219], v96, s[44:45] offset:16
	global_load_dwordx4 v[220:223], v96, s[4:5] offset:16
	v_mov_b32_e32 v96, v76
	v_mov_b32_e32 v104, v76
	s_nop 1
	v_permlane16_swap_b32_e32 v96, v104
	v_cndmask_b32_e64 v96, v96, v104, s[6:7]
	v_cndmask_b32_e64 v105, v96, -v96, s[10:11]
	v_mov_b32_e32 v96, v77
	v_mov_b32_e32 v106, v76
	s_waitcnt vmcnt(2)
	v_mov_b32_e32 v104, v208
	v_mov_b32_e32 v107, v212
	v_mov_b32_e32 v98, v77
	s_nop 1
	v_permlane16_swap_b32_e32 v96, v98
	v_pk_mul_f32 v[104:105], v[106:107], v[104:105]
	v_cndmask_b32_e64 v96, v96, v98, s[6:7]
	v_add_f32_e32 v80, v104, v105
	v_cndmask_b32_e64 v105, v96, -v96, s[10:11]
	v_mov_b32_e32 v98, v77
	v_mov_b32_e32 v104, v209
	v_mov_b32_e32 v99, v213
	v_pk_mul_f32 v[98:99], v[98:99], v[104:105]
	v_mov_b32_e32 v96, v78
	v_add_f32_e32 v81, v98, v99
	v_mov_b32_e32 v98, v78
	s_nop 1
	v_permlane16_swap_b32_e32 v96, v98
	v_cndmask_b32_e64 v96, v96, v98, s[6:7]
	v_cndmask_b32_e64 v99, v96, -v96, s[10:11]
	v_mov_b32_e32 v104, v78
	v_mov_b32_e32 v105, v214
	v_mov_b32_e32 v98, v210
	v_pk_mul_f32 v[98:99], v[104:105], v[98:99]
	v_mov_b32_e32 v96, v79
	v_add_f32_e32 v82, v98, v99
	v_mov_b32_e32 v98, v79
	s_nop 1
	v_permlane16_swap_b32_e32 v96, v98
	v_cndmask_b32_e64 v96, v96, v98, s[6:7]
	v_cndmask_b32_e64 v99, v96, -v96, s[10:11]
	v_mov_b32_e32 v100, v79
	v_mov_b32_e32 v98, v211
	v_mov_b32_e32 v101, v215
	v_pk_mul_f32 v[98:99], v[100:101], v[98:99]
	v_cndmask_b32_e64 v80, v76, v80, s[8:9]
	v_add_f32_e32 v83, v98, v99
	v_cndmask_b32_e64 v81, v77, v81, s[8:9]
	v_cndmask_b32_e64 v82, v78, v82, s[8:9]
	v_cndmask_b32_e64 v83, v79, v83, s[8:9]
	v_mov_b32_e32 v104, v80
	v_mov_b32_e32 v106, v81
	v_mov_b32_e32 v105, v82
	v_mov_b32_e32 v107, v83
	v_lshl_add_u64 v[80:81], s[82:83], 0, v[84:85]
	v_lshl_add_u64 v[80:81], s[0:1], 1, v[80:81]
	v_lshlrev_b32_e32 v96, 1, v142
	v_lshl_add_u64 v[80:81], v[80:81], 0, v[96:97]
	v_cvt_pk_bf16_f32 v82, v104, v106
	v_cvt_pk_bf16_f32 v83, v105, v107
	global_store_dwordx2 v[80:81], v[82:83], off offset:-1024
	v_lshlrev_b32_e32 v82, 2, v103
	v_mov_b32_e32 v82, v72
	v_mov_b32_e32 v83, v72
	s_nop 1
	v_permlane16_swap_b32_e32 v82, v83
	v_cndmask_b32_e64 v82, v82, v83, s[6:7]
	v_cndmask_b32_e64 v83, v82, -v82, s[10:11]
	v_mov_b32_e32 v104, v72
	s_waitcnt vmcnt(1)
; __device__ __forceinline__ float shx16(float v, int odd  ) { const unsigned x = __builtin_bit_cast(unsigned, v); auto r = __builtin_amdgcn_permlane16_swap(x, x, false, false); return __builtin_bit_cast(float, odd ? r[0] : r[1]); }
; __device__ __forceinline__ void st_bf4(bf16_t* p, const f32x4 v) { u32x2 w; w.x = cvt_pk_bf16(v[0], v[1]); w.y = cvt_pk_bf16(v[2], v[3]); *(u32x2*)p = w; }
;     __device__ __forceinline__ void operator()(const f32x4 (&acc)[2][2][4][2], const Unit& u, int wr, int wc, int fr, int fq) const {
;     ...
;             for (int m = 0; m < 4; ++m) { const int row = u.pm * 256 + ai * 128 + wr * 64 + m * 16 + fr;
; #pragma unroll
;                 for (int bj = 0; bj < 2; ++bj)
; #pragma unroll
;                     for (int n = 0; n < 2; ++n) { const int tc = bj * 128 + wc * 32 + 8 * fq + 4 * n; f32x4 v = acc[ai][bj][m][n];
;                         if (pn < 2) { *(f32x4*)(XA + (size_t)row * 512 + pn * 256 + tc) = v; }
;                         else if (pn <= 4) {
;                             const bool isv = (pn == 4 && bj == 1);
;                             if (!isv && (wc & 1) == 0) {
;                                 const int tix = row < cfg::MP ? (row & 2047) : 2048 + (row & 3);
;                                 const f32x4 cs = *(const f32x4*)(ropec + tix * 8 + 4 * n), sn = *(const f32x4*)(ropes + tix * 8 + 4 * n);
; #pragma unroll
;                                 for (int i = 0; i < 4; ++i) { const float p = shx16(v[i], fq & 1); const float rv = v[i] * cs[i] + (fq == 0 ? -p : p) * sn[i]; v[i] = fq < 2 ? rv : v[i]; }
;                             }
;                             if (pn < 4) st_bf4(Q + (size_t)row * 512 + (pn - 2) * 256 + tc, v);
	v_mov_b32_e32 v82, v216
	v_mov_b32_e32 v105, v220
	v_pk_mul_f32 v[82:83], v[104:105], v[82:83]
	v_mov_b32_e32 v98, v73
	v_add_f32_e32 v76, v82, v83
	v_mov_b32_e32 v82, v73
	v_mov_b32_e32 v83, v73
	s_nop 1
	v_permlane16_swap_b32_e32 v82, v83
	v_cndmask_b32_e64 v82, v82, v83, s[6:7]
	v_cndmask_b32_e64 v83, v82, -v82, s[10:11]
	v_mov_b32_e32 v82, v217
	v_mov_b32_e32 v99, v221
	v_pk_mul_f32 v[82:83], v[98:99], v[82:83]
	v_mov_b32_e32 v98, v74
	v_add_f32_e32 v77, v82, v83
	v_mov_b32_e32 v82, v74
	v_mov_b32_e32 v83, v74
	s_nop 1
	v_permlane16_swap_b32_e32 v82, v83
	v_cndmask_b32_e64 v82, v82, v83, s[6:7]
	v_cndmask_b32_e64 v83, v82, -v82, s[10:11]
	v_mov_b32_e32 v99, v222
	v_mov_b32_e32 v82, v218
	v_pk_mul_f32 v[82:83], v[98:99], v[82:83]
	v_mov_b32_e32 v100, v75
	v_add_f32_e32 v78, v82, v83
	v_mov_b32_e32 v82, v75
	v_mov_b32_e32 v83, v75
	s_nop 1
	v_permlane16_swap_b32_e32 v82, v83
	v_cndmask_b32_e64 v82, v82, v83, s[6:7]
	v_cndmask_b32_e64 v83, v82, -v82, s[10:11]
	v_mov_b32_e32 v82, v219
	v_mov_b32_e32 v101, v223
	v_pk_mul_f32 v[82:83], v[100:101], v[82:83]
	v_cndmask_b32_e64 v76, v72, v76, s[8:9]
	v_add_f32_e32 v79, v82, v83
	v_cndmask_b32_e64 v77, v73, v77, s[8:9]
	v_cndmask_b32_e64 v78, v74, v78, s[8:9]
	v_cndmask_b32_e64 v79, v75, v79, s[8:9]
	v_mov_b32_e32 v100, v76
	v_mov_b32_e32 v104, v77
	v_mov_b32_e32 v101, v78
	v_mov_b32_e32 v105, v79
	v_lshl_add_u64 v[76:77], s[82:83], 0, v[84:85]
	v_lshl_add_u64 v[76:77], s[0:1], 1, v[76:77]
	v_lshlrev_b32_e32 v96, 1, v142
	v_lshl_add_u64 v[76:77], v[76:77], 0, v[96:97]
	v_cvt_pk_bf16_f32 v78, v100, v104
	v_cvt_pk_bf16_f32 v79, v101, v105
	global_store_dwordx2 v[76:77], v[78:79], off offset:-1016
	v_lshlrev_b32_e32 v78, 2, v103
	v_mov_b32_e32 v78, v68
	v_mov_b32_e32 v79, v68
	s_nop 1
	v_permlane16_swap_b32_e32 v78, v79
	v_cndmask_b32_e64 v78, v78, v79, s[6:7]
	v_cndmask_b32_e64 v79, v78, -v78, s[10:11]
	v_mov_b32_e32 v82, v68
	v_mov_b32_e32 v78, v208
	v_mov_b32_e32 v83, v212
	v_pk_mul_f32 v[78:79], v[82:83], v[78:79]
	v_mov_b32_e32 v92, v69
	v_add_f32_e32 v72, v78, v79
	v_mov_b32_e32 v78, v69
	v_mov_b32_e32 v79, v69
	s_nop 1
	v_permlane16_swap_b32_e32 v78, v79
	v_cndmask_b32_e64 v78, v78, v79, s[6:7]
	v_cndmask_b32_e64 v79, v78, -v78, s[10:11]
	v_mov_b32_e32 v78, v209
	v_mov_b32_e32 v93, v213
	v_pk_mul_f32 v[78:79], v[92:93], v[78:79]
	v_mov_b32_e32 v82, v70
	v_add_f32_e32 v73, v78, v79
	v_mov_b32_e32 v78, v70
	v_mov_b32_e32 v79, v70
	s_nop 1
	v_permlane16_swap_b32_e32 v78, v79
	v_cndmask_b32_e64 v78, v78, v79, s[6:7]
	v_cndmask_b32_e64 v79, v78, -v78, s[10:11]
	v_mov_b32_e32 v83, v214
	v_mov_b32_e32 v78, v210
	v_pk_mul_f32 v[78:79], v[82:83], v[78:79]
	v_mov_b32_e32 v94, v71
	v_add_f32_e32 v74, v78, v79
	v_mov_b32_e32 v78, v71
	v_mov_b32_e32 v79, v71
	s_nop 1
	v_permlane16_swap_b32_e32 v78, v79
	v_cndmask_b32_e64 v78, v78, v79, s[6:7]
	v_cndmask_b32_e64 v79, v78, -v78, s[10:11]
	v_mov_b32_e32 v78, v211
	v_mov_b32_e32 v95, v215
	v_pk_mul_f32 v[78:79], v[94:95], v[78:79]
	v_cndmask_b32_e64 v72, v68, v72, s[8:9]
	v_add_f32_e32 v75, v78, v79
	v_cndmask_b32_e64 v73, v69, v73, s[8:9]
	v_cndmask_b32_e64 v74, v70, v74, s[8:9]
	v_cndmask_b32_e64 v75, v71, v75, s[8:9]
	v_mov_b32_e32 v92, v72
	v_mov_b32_e32 v94, v73
	v_mov_b32_e32 v93, v74
	v_mov_b32_e32 v95, v75
	v_lshl_add_u64 v[72:73], s[82:83], 0, v[84:85]
	v_lshl_add_u64 v[72:73], s[0:1], 1, v[72:73]
	v_lshlrev_b32_e32 v96, 1, v142
	v_lshl_add_u64 v[72:73], v[72:73], 0, v[96:97]
	v_cvt_pk_bf16_f32 v74, v92, v94
	v_cvt_pk_bf16_f32 v75, v93, v95
	global_store_dwordx2 v[72:73], v[74:75], off offset:-768
	v_lshlrev_b32_e32 v72, 2, v103
	v_mov_b32_e32 v78, v64
	v_mov_b32_e32 v79, v64
	s_nop 1
	v_permlane16_swap_b32_e32 v78, v79
	v_cndmask_b32_e64 v78, v78, v79, s[6:7]
	v_cndmask_b32_e64 v79, v78, -v78, s[10:11]
	v_mov_b32_e32 v82, v64
	v_mov_b32_e32 v78, v216
	v_mov_b32_e32 v83, v220
	v_pk_mul_f32 v[78:79], v[82:83], v[78:79]
	v_mov_b32_e32 v72, v65
	v_add_f32_e32 v68, v78, v79
	v_mov_b32_e32 v78, v65
	s_nop 1
	v_permlane16_swap_b32_e32 v72, v78
	v_cndmask_b32_e64 v72, v72, v78, s[6:7]
	v_cndmask_b32_e64 v79, v72, -v72, s[10:11]
	v_mov_b32_e32 v72, v65
	v_mov_b32_e32 v78, v217
	v_mov_b32_e32 v73, v221
	v_pk_mul_f32 v[72:73], v[72:73], v[78:79]
	v_mov_b32_e32 v78, v66
	v_add_f32_e32 v69, v72, v73
	v_mov_b32_e32 v72, v66
	v_mov_b32_e32 v73, v66
	s_nop 1
	v_permlane16_swap_b32_e32 v72, v73
	v_cndmask_b32_e64 v72, v72, v73, s[6:7]
	v_cndmask_b32_e64 v73, v72, -v72, s[10:11]
	v_mov_b32_e32 v79, v222
	v_mov_b32_e32 v72, v218
	v_pk_mul_f32 v[72:73], v[78:79], v[72:73]
	v_mov_b32_e32 v74, v67
	v_add_f32_e32 v70, v72, v73
	v_mov_b32_e32 v72, v67
	v_mov_b32_e32 v73, v67
	s_nop 1
	v_permlane16_swap_b32_e32 v72, v73
	v_cndmask_b32_e64 v72, v72, v73, s[6:7]
	v_cndmask_b32_e64 v73, v72, -v72, s[10:11]
	v_mov_b32_e32 v72, v219
	v_mov_b32_e32 v75, v223
	v_pk_mul_f32 v[72:73], v[74:75], v[72:73]
	v_cndmask_b32_e64 v68, v64, v68, s[8:9]
	v_add_f32_e32 v71, v72, v73
	v_cndmask_b32_e64 v69, v65, v69, s[8:9]
	v_cndmask_b32_e64 v70, v66, v70, s[8:9]
	v_cndmask_b32_e64 v71, v67, v71, s[8:9]
	v_mov_b32_e32 v78, v68
	v_mov_b32_e32 v82, v69
	v_mov_b32_e32 v79, v70
	v_mov_b32_e32 v83, v71
	s_mov_b64 s[70:71], -1
	s_andn2_b64 vcc, exec, s[70:71]
	v_lshl_add_u64 v[68:69], s[82:83], 0, v[84:85]
	v_lshl_add_u64 v[68:69], s[0:1], 1, v[68:69]
	v_lshlrev_b32_e32 v96, 1, v142
	v_lshl_add_u64 v[68:69], v[68:69], 0, v[96:97]
	v_cvt_pk_bf16_f32 v70, v78, v82
	v_cvt_pk_bf16_f32 v71, v79, v83
	global_store_dwordx2 v[68:69], v[70:71], off offset:-760
	s_add_i32 s46, s53, 0x80
	v_or_b32_e32 v68, s46, v143
	v_mad_i64_i32 v[76:77], s[18:19], v68, s61, 0
	v_mov_b32_e32 v64, 0x7cf
	s_movk_i32 s18, 0x4000
	v_bitop3_b32 v64, s46, v64, v143 bitop3:0xc8
	v_cmp_gt_i32_e32 vcc, s18, v68
	v_ashrrev_i32_e32 v69, 31, v68
	s_nop 0
	v_cndmask_b32_e32 v65, v151, v64, vcc
	v_lshlrev_b32_e32 v87, 3, v65
	v_add_u32_e32 v65, 0xffffc000, v68
	v_lshrrev_b32_e32 v86, 2, v65
	v_lshlrev_b64 v[70:71], 10, v[68:69]
	s_mov_b32 s75, 0x400000
	v_lshlrev_b32_e32 v69, 2, v87
	global_load_dwordx4 v[208:211], v69, s[44:45]
	global_load_dwordx4 v[212:215], v69, s[4:5]
	global_load_dwordx4 v[216:219], v69, s[44:45] offset:16
	global_load_dwordx4 v[220:223], v69, s[4:5] offset:16
	v_mov_b32_e32 v69, v60
	v_mov_b32_e32 v88, v60
	s_nop 1
	v_permlane16_swap_b32_e32 v69, v88
	v_cndmask_b32_e64 v69, v69, v88, s[6:7]
	v_cndmask_b32_e64 v89, v69, -v69, s[10:11]
	v_mov_b32_e32 v69, v61
	v_mov_b32_e32 v90, v60
	s_waitcnt vmcnt(2)
; __device__ __forceinline__ float shx16(float v, int odd  ) { const unsigned x = __builtin_bit_cast(unsigned, v); auto r = __builtin_amdgcn_permlane16_swap(x, x, false, false); return __builtin_bit_cast(float, odd ? r[0] : r[1]); }
; __device__ __forceinline__ void st_bf4(bf16_t* p, const f32x4 v) { u32x2 w; w.x = cvt_pk_bf16(v[0], v[1]); w.y = cvt_pk_bf16(v[2], v[3]); *(u32x2*)p = w; }
;     __device__ __forceinline__ void operator()(const f32x4 (&acc)[2][2][4][2], const Unit& u, int wr, int wc, int fr, int fq) const {
;     ...
;             for (int m = 0; m < 4; ++m) { const int row = u.pm * 256 + ai * 128 + wr * 64 + m * 16 + fr;
; #pragma unroll
;                 for (int bj = 0; bj < 2; ++bj)
; #pragma unroll
;                     for (int n = 0; n < 2; ++n) { const int tc = bj * 128 + wc * 32 + 8 * fq + 4 * n; f32x4 v = acc[ai][bj][m][n];
;                         if (pn < 2) { *(f32x4*)(XA + (size_t)row * 512 + pn * 256 + tc) = v; }
;                         else if (pn <= 4) {
;                             const bool isv = (pn == 4 && bj == 1);
;                             if (!isv && (wc & 1) == 0) {
;                                 const int tix = row < cfg::MP ? (row & 2047) : 2048 + (row & 3);
;                                 const f32x4 cs = *(const f32x4*)(ropec + tix * 8 + 4 * n), sn = *(const f32x4*)(ropes + tix * 8 + 4 * n);
; #pragma unroll
;                                 for (int i = 0; i < 4; ++i) { const float p = shx16(v[i], fq & 1); const float rv = v[i] * cs[i] + (fq == 0 ? -p : p) * sn[i]; v[i] = fq < 2 ? rv : v[i]; }
;                             }
;                             if (pn < 4) st_bf4(Q + (size_t)row * 512 + (pn - 2) * 256 + tc, v);
	v_mov_b32_e32 v88, v208
	v_mov_b32_e32 v91, v212
	v_mov_b32_e32 v82, v61
	s_nop 1
	v_permlane16_swap_b32_e32 v69, v82
	v_pk_mul_f32 v[88:89], v[90:91], v[88:89]
	v_cndmask_b32_e64 v69, v69, v82, s[6:7]
	v_add_f32_e32 v64, v88, v89
	v_cndmask_b32_e64 v89, v69, -v69, s[10:11]
	v_mov_b32_e32 v82, v61
	v_mov_b32_e32 v88, v209
	v_mov_b32_e32 v83, v213
	v_pk_mul_f32 v[82:83], v[82:83], v[88:89]
	v_mov_b32_e32 v69, v62
	v_add_f32_e32 v65, v82, v83
	v_mov_b32_e32 v82, v62
	s_nop 1
	v_permlane16_swap_b32_e32 v69, v82
	v_cndmask_b32_e64 v69, v69, v82, s[6:7]
	v_cndmask_b32_e64 v83, v69, -v69, s[10:11]
	v_mov_b32_e32 v88, v62
	v_mov_b32_e32 v89, v214
	v_mov_b32_e32 v82, v210
	v_pk_mul_f32 v[82:83], v[88:89], v[82:83]
	v_mov_b32_e32 v69, v63
	v_add_f32_e32 v66, v82, v83
	v_mov_b32_e32 v82, v63
	s_nop 1
	v_permlane16_swap_b32_e32 v69, v82
	v_cndmask_b32_e64 v69, v69, v82, s[6:7]
	v_cndmask_b32_e64 v83, v69, -v69, s[10:11]
	v_mov_b32_e32 v84, v63
	v_mov_b32_e32 v82, v211
	v_mov_b32_e32 v85, v215
	v_pk_mul_f32 v[82:83], v[84:85], v[82:83]
	v_cndmask_b32_e64 v64, v60, v64, s[8:9]
	v_add_f32_e32 v67, v82, v83
	v_cndmask_b32_e64 v65, v61, v65, s[8:9]
	v_cndmask_b32_e64 v66, v62, v66, s[8:9]
	v_cndmask_b32_e64 v67, v63, v67, s[8:9]
	v_mov_b32_e32 v69, v64
	v_mov_b32_e32 v89, v65
	v_mov_b32_e32 v88, v66
	v_mov_b32_e32 v90, v67
	v_lshl_add_u64 v[64:65], s[82:83], 0, v[70:71]
	v_lshl_add_u64 v[64:65], s[0:1], 1, v[64:65]
	v_lshlrev_b32_e32 v96, 1, v142
	v_lshl_add_u64 v[64:65], v[64:65], 0, v[96:97]
	v_cvt_pk_bf16_f32 v66, v69, v89
	v_cvt_pk_bf16_f32 v67, v88, v90
	global_store_dwordx2 v[64:65], v[66:67], off offset:-1024
	v_lshlrev_b32_e32 v66, 2, v87
	v_mov_b32_e32 v66, v56
	v_mov_b32_e32 v67, v56
	s_nop 1
	v_permlane16_swap_b32_e32 v66, v67
	v_cndmask_b32_e64 v66, v66, v67, s[6:7]
	v_cndmask_b32_e64 v67, v66, -v66, s[10:11]
	v_mov_b32_e32 v88, v56
	s_waitcnt vmcnt(1)
	v_mov_b32_e32 v66, v216
	v_mov_b32_e32 v89, v220
	v_pk_mul_f32 v[66:67], v[88:89], v[66:67]
	v_mov_b32_e32 v82, v57
	v_add_f32_e32 v60, v66, v67
	v_mov_b32_e32 v66, v57
	v_mov_b32_e32 v67, v57
	s_nop 1
	v_permlane16_swap_b32_e32 v66, v67
	v_cndmask_b32_e64 v66, v66, v67, s[6:7]
	v_cndmask_b32_e64 v67, v66, -v66, s[10:11]
	v_mov_b32_e32 v66, v217
	v_mov_b32_e32 v83, v221
	v_pk_mul_f32 v[66:67], v[82:83], v[66:67]
	v_mov_b32_e32 v82, v58
	v_add_f32_e32 v61, v66, v67
	v_mov_b32_e32 v66, v58
	v_mov_b32_e32 v67, v58
	s_nop 1
	v_permlane16_swap_b32_e32 v66, v67
	v_cndmask_b32_e64 v66, v66, v67, s[6:7]
	v_cndmask_b32_e64 v67, v66, -v66, s[10:11]
	v_mov_b32_e32 v83, v222
	v_mov_b32_e32 v66, v218
	v_pk_mul_f32 v[66:67], v[82:83], v[66:67]
	v_mov_b32_e32 v84, v59
	v_add_f32_e32 v62, v66, v67
	v_mov_b32_e32 v66, v59
	v_mov_b32_e32 v67, v59
	s_nop 1
	v_permlane16_swap_b32_e32 v66, v67
	v_cndmask_b32_e64 v66, v66, v67, s[6:7]
	v_cndmask_b32_e64 v67, v66, -v66, s[10:11]
	v_mov_b32_e32 v66, v219
	v_mov_b32_e32 v85, v223
	v_pk_mul_f32 v[66:67], v[84:85], v[66:67]
	v_cndmask_b32_e64 v60, v56, v60, s[8:9]
	v_add_f32_e32 v63, v66, v67
	v_cndmask_b32_e64 v61, v57, v61, s[8:9]
	v_cndmask_b32_e64 v62, v58, v62, s[8:9]
	v_cndmask_b32_e64 v63, v59, v63, s[8:9]
	v_mov_b32_e32 v69, v60
	v_mov_b32_e32 v85, v61
	v_mov_b32_e32 v84, v62
	v_mov_b32_e32 v88, v63
	v_lshl_add_u64 v[60:61], s[82:83], 0, v[70:71]
	v_lshl_add_u64 v[60:61], s[0:1], 1, v[60:61]
	v_lshlrev_b32_e32 v96, 1, v142
	v_lshl_add_u64 v[60:61], v[60:61], 0, v[96:97]
	v_cvt_pk_bf16_f32 v62, v69, v85
	v_cvt_pk_bf16_f32 v63, v84, v88
	global_store_dwordx2 v[60:61], v[62:63], off offset:-1016
	v_lshlrev_b32_e32 v62, 2, v87
	v_mov_b32_e32 v62, v52
	v_mov_b32_e32 v63, v52
	s_nop 1
	v_permlane16_swap_b32_e32 v62, v63
	v_cndmask_b32_e64 v62, v62, v63, s[6:7]
	v_cndmask_b32_e64 v63, v62, -v62, s[10:11]
	v_mov_b32_e32 v66, v52
	v_mov_b32_e32 v62, v208
	v_mov_b32_e32 v67, v212
	v_pk_mul_f32 v[62:63], v[66:67], v[62:63]
	v_mov_b32_e32 v78, v53
	v_add_f32_e32 v56, v62, v63
	v_mov_b32_e32 v62, v53
	v_mov_b32_e32 v63, v53
	s_nop 1
	v_permlane16_swap_b32_e32 v62, v63
	v_cndmask_b32_e64 v62, v62, v63, s[6:7]
	v_cndmask_b32_e64 v63, v62, -v62, s[10:11]
	v_mov_b32_e32 v62, v209
	v_mov_b32_e32 v79, v213
	v_pk_mul_f32 v[62:63], v[78:79], v[62:63]
	v_mov_b32_e32 v66, v54
	v_add_f32_e32 v57, v62, v63
	v_mov_b32_e32 v62, v54
	v_mov_b32_e32 v63, v54
	s_nop 1
	v_permlane16_swap_b32_e32 v62, v63
	v_cndmask_b32_e64 v62, v62, v63, s[6:7]
	v_cndmask_b32_e64 v63, v62, -v62, s[10:11]
	v_mov_b32_e32 v67, v214
	v_mov_b32_e32 v62, v210
	v_pk_mul_f32 v[62:63], v[66:67], v[62:63]
	v_mov_b32_e32 v80, v55
	v_add_f32_e32 v58, v62, v63
	v_mov_b32_e32 v62, v55
	v_mov_b32_e32 v63, v55
	s_nop 1
	v_permlane16_swap_b32_e32 v62, v63
	v_cndmask_b32_e64 v62, v62, v63, s[6:7]
	v_cndmask_b32_e64 v63, v62, -v62, s[10:11]
	v_mov_b32_e32 v62, v211
	v_mov_b32_e32 v81, v215
	v_pk_mul_f32 v[62:63], v[80:81], v[62:63]
	v_cndmask_b32_e64 v56, v52, v56, s[8:9]
	v_add_f32_e32 v59, v62, v63
	v_cndmask_b32_e64 v57, v53, v57, s[8:9]
	v_cndmask_b32_e64 v58, v54, v58, s[8:9]
	v_cndmask_b32_e64 v59, v55, v59, s[8:9]
	v_mov_b32_e32 v69, v56
	v_mov_b32_e32 v79, v57
	v_mov_b32_e32 v78, v58
	v_mov_b32_e32 v80, v59
	v_lshl_add_u64 v[56:57], s[82:83], 0, v[70:71]
	v_lshl_add_u64 v[56:57], s[0:1], 1, v[56:57]
	v_lshlrev_b32_e32 v96, 1, v142
	v_lshl_add_u64 v[56:57], v[56:57], 0, v[96:97]
	v_cvt_pk_bf16_f32 v58, v69, v79
	v_cvt_pk_bf16_f32 v59, v78, v80
	global_store_dwordx2 v[56:57], v[58:59], off offset:-768
	v_lshlrev_b32_e32 v56, 2, v87
	v_mov_b32_e32 v62, v48
	v_mov_b32_e32 v63, v48
	s_nop 1
	v_permlane16_swap_b32_e32 v62, v63
	v_cndmask_b32_e64 v62, v62, v63, s[6:7]
	v_cndmask_b32_e64 v63, v62, -v62, s[10:11]
; __device__ __forceinline__ float shx16(float v, int odd  ) { const unsigned x = __builtin_bit_cast(unsigned, v); auto r = __builtin_amdgcn_permlane16_swap(x, x, false, false); return __builtin_bit_cast(float, odd ? r[0] : r[1]); }
; __device__ __forceinline__ void st_bf4(bf16_t* p, const f32x4 v) { u32x2 w; w.x = cvt_pk_bf16(v[0], v[1]); w.y = cvt_pk_bf16(v[2], v[3]); *(u32x2*)p = w; }
;     __device__ __forceinline__ void operator()(const f32x4 (&acc)[2][2][4][2], const Unit& u, int wr, int wc, int fr, int fq) const {
;     ...
;             for (int m = 0; m < 4; ++m) { const int row = u.pm * 256 + ai * 128 + wr * 64 + m * 16 + fr;
; #pragma unroll
;                 for (int bj = 0; bj < 2; ++bj)
; #pragma unroll
;                     for (int n = 0; n < 2; ++n) { const int tc = bj * 128 + wc * 32 + 8 * fq + 4 * n; f32x4 v = acc[ai][bj][m][n];
;                         if (pn < 2) { *(f32x4*)(XA + (size_t)row * 512 + pn * 256 + tc) = v; }
;                         else if (pn <= 4) {
;                             const bool isv = (pn == 4 && bj == 1);
;                             if (!isv && (wc & 1) == 0) {
;                                 const int tix = row < cfg::MP ? (row & 2047) : 2048 + (row & 3);
;                                 const f32x4 cs = *(const f32x4*)(ropec + tix * 8 + 4 * n), sn = *(const f32x4*)(ropes + tix * 8 + 4 * n);
; #pragma unroll
;                                 for (int i = 0; i < 4; ++i) { const float p = shx16(v[i], fq & 1); const float rv = v[i] * cs[i] + (fq == 0 ? -p : p) * sn[i]; v[i] = fq < 2 ? rv : v[i]; }
;                             }
;                             if (pn < 4) st_bf4(Q + (size_t)row * 512 + (pn - 2) * 256 + tc, v);
	v_mov_b32_e32 v66, v48
	v_mov_b32_e32 v62, v216
	v_mov_b32_e32 v67, v220
	v_pk_mul_f32 v[62:63], v[66:67], v[62:63]
	v_mov_b32_e32 v56, v49
	v_add_f32_e32 v52, v62, v63
	v_mov_b32_e32 v62, v49
	s_nop 1
	v_permlane16_swap_b32_e32 v56, v62
	v_cndmask_b32_e64 v56, v56, v62, s[6:7]
	v_cndmask_b32_e64 v63, v56, -v56, s[10:11]
	v_mov_b32_e32 v56, v49
	v_mov_b32_e32 v62, v217
	v_mov_b32_e32 v57, v221
	v_pk_mul_f32 v[56:57], v[56:57], v[62:63]
	v_mov_b32_e32 v62, v50
	v_add_f32_e32 v53, v56, v57
	v_mov_b32_e32 v56, v50
	v_mov_b32_e32 v57, v50
	s_nop 1
	v_permlane16_swap_b32_e32 v56, v57
	v_cndmask_b32_e64 v56, v56, v57, s[6:7]
	v_cndmask_b32_e64 v57, v56, -v56, s[10:11]
	v_mov_b32_e32 v63, v222
	v_mov_b32_e32 v56, v218
	v_pk_mul_f32 v[56:57], v[62:63], v[56:57]
	v_mov_b32_e32 v58, v51
	v_add_f32_e32 v54, v56, v57
	v_mov_b32_e32 v56, v51
	v_mov_b32_e32 v57, v51
	s_nop 1
	v_permlane16_swap_b32_e32 v56, v57
	v_cndmask_b32_e64 v56, v56, v57, s[6:7]
	v_cndmask_b32_e64 v57, v56, -v56, s[10:11]
	v_mov_b32_e32 v56, v219
	v_mov_b32_e32 v59, v223
	v_pk_mul_f32 v[56:57], v[58:59], v[56:57]
	v_cndmask_b32_e64 v52, v48, v52, s[8:9]
	v_add_f32_e32 v55, v56, v57
	v_cndmask_b32_e64 v53, v49, v53, s[8:9]
	v_cndmask_b32_e64 v54, v50, v54, s[8:9]
	v_cndmask_b32_e64 v55, v51, v55, s[8:9]
	v_mov_b32_e32 v62, v52
	v_mov_b32_e32 v66, v53
	v_mov_b32_e32 v63, v54
	v_mov_b32_e32 v67, v55
	s_mov_b64 s[70:71], -1
	s_andn2_b64 vcc, exec, s[70:71]
	v_lshl_add_u64 v[52:53], s[82:83], 0, v[70:71]
	v_lshl_add_u64 v[52:53], s[0:1], 1, v[52:53]
	v_lshlrev_b32_e32 v96, 1, v142
	v_lshl_add_u64 v[52:53], v[52:53], 0, v[96:97]
	v_cvt_pk_bf16_f32 v54, v62, v66
	v_cvt_pk_bf16_f32 v55, v63, v67
	global_store_dwordx2 v[52:53], v[54:55], off offset:-760
	v_or_b32_e32 v48, 16, v68
	v_mad_i64_i32 v[58:59], s[18:19], v48, s61, 0
	s_movk_i32 s18, 0x7df
	s_nop 0
	v_bitop3_b32 v50, v68, s18, 16 bitop3:0xc8
	s_movk_i32 s18, 0x4000
	v_cmp_gt_i32_e32 vcc, s18, v48
	v_ashrrev_i32_e32 v49, 31, v48
	s_nop 0
	v_cndmask_b32_e32 v51, v151, v50, vcc
	v_lshlrev_b32_e32 v70, 3, v51
	v_add_u32_e32 v51, 0xffffc010, v68
	v_lshrrev_b32_e32 v69, 2, v51
	v_lshlrev_b64 v[52:53], 10, v[48:49]
	v_lshlrev_b32_e32 v64, 2, v70
	global_load_dwordx4 v[208:211], v64, s[44:45]
	global_load_dwordx4 v[212:215], v64, s[4:5]
	global_load_dwordx4 v[216:219], v64, s[44:45] offset:16
	global_load_dwordx4 v[220:223], v64, s[4:5] offset:16
	v_mov_b32_e32 v71, v44
	v_mov_b32_e32 v72, v44
	s_nop 1
	v_permlane16_swap_b32_e32 v71, v72
	v_cndmask_b32_e64 v71, v71, v72, s[6:7]
	v_cndmask_b32_e64 v73, v71, -v71, s[10:11]
	v_mov_b32_e32 v71, v45
	v_mov_b32_e32 v74, v44
	s_waitcnt vmcnt(2)
	v_mov_b32_e32 v72, v208
	v_mov_b32_e32 v75, v212
	v_mov_b32_e32 v64, v45
	s_nop 1
	v_permlane16_swap_b32_e32 v64, v71
	v_pk_mul_f32 v[72:73], v[74:75], v[72:73]
	v_cndmask_b32_e64 v64, v64, v71, s[6:7]
	v_add_f32_e32 v48, v72, v73
	v_cndmask_b32_e64 v73, v64, -v64, s[10:11]
	v_mov_b32_e32 v64, v45
	v_mov_b32_e32 v72, v209
	v_mov_b32_e32 v65, v213
	v_pk_mul_f32 v[64:65], v[64:65], v[72:73]
	v_mov_b32_e32 v72, v46
	v_add_f32_e32 v49, v64, v65
	v_mov_b32_e32 v64, v46
	v_mov_b32_e32 v65, v46
	s_nop 1
	v_permlane16_swap_b32_e32 v64, v65
	v_cndmask_b32_e64 v64, v64, v65, s[6:7]
	v_cndmask_b32_e64 v65, v64, -v64, s[10:11]
	v_mov_b32_e32 v73, v214
	v_mov_b32_e32 v64, v210
	v_pk_mul_f32 v[64:65], v[72:73], v[64:65]
	v_mov_b32_e32 v66, v47
	v_add_f32_e32 v50, v64, v65
	v_mov_b32_e32 v64, v47
	v_mov_b32_e32 v65, v47
	s_nop 1
	v_permlane16_swap_b32_e32 v64, v65
	v_cndmask_b32_e64 v64, v64, v65, s[6:7]
	v_cndmask_b32_e64 v65, v64, -v64, s[10:11]
	v_mov_b32_e32 v64, v211
	v_mov_b32_e32 v67, v215
	v_pk_mul_f32 v[64:65], v[66:67], v[64:65]
	v_cndmask_b32_e64 v48, v44, v48, s[8:9]
	v_add_f32_e32 v51, v64, v65
	v_cndmask_b32_e64 v49, v45, v49, s[8:9]
	v_cndmask_b32_e64 v50, v46, v50, s[8:9]
	v_cndmask_b32_e64 v51, v47, v51, s[8:9]
	v_mov_b32_e32 v71, v48
	v_mov_b32_e32 v73, v49
	v_mov_b32_e32 v72, v50
	v_mov_b32_e32 v74, v51
	v_lshl_add_u64 v[48:49], s[82:83], 0, v[52:53]
	v_lshl_add_u64 v[48:49], s[0:1], 1, v[48:49]
	v_lshlrev_b32_e32 v96, 1, v142
	v_lshl_add_u64 v[48:49], v[48:49], 0, v[96:97]
	v_cvt_pk_bf16_f32 v50, v71, v73
	v_cvt_pk_bf16_f32 v51, v72, v74
	global_store_dwordx2 v[48:49], v[50:51], off offset:-1024
	v_lshlrev_b32_e32 v50, 2, v70
	v_mov_b32_e32 v50, v40
	v_mov_b32_e32 v51, v40
	s_nop 1
	v_permlane16_swap_b32_e32 v50, v51
	v_cndmask_b32_e64 v50, v50, v51, s[6:7]
	v_cndmask_b32_e64 v51, v50, -v50, s[10:11]
	v_mov_b32_e32 v72, v40
	s_waitcnt vmcnt(1)
; __device__ __forceinline__ float shx16(float v, int odd  ) { const unsigned x = __builtin_bit_cast(unsigned, v); auto r = __builtin_amdgcn_permlane16_swap(x, x, false, false); return __builtin_bit_cast(float, odd ? r[0] : r[1]); }
; __device__ __forceinline__ void st_bf4(bf16_t* p, const f32x4 v) { u32x2 w; w.x = cvt_pk_bf16(v[0], v[1]); w.y = cvt_pk_bf16(v[2], v[3]); *(u32x2*)p = w; }
;     __device__ __forceinline__ void operator()(const f32x4 (&acc)[2][2][4][2], const Unit& u, int wr, int wc, int fr, int fq) const {
;     ...
;             for (int m = 0; m < 4; ++m) { const int row = u.pm * 256 + ai * 128 + wr * 64 + m * 16 + fr;
; #pragma unroll
;                 for (int bj = 0; bj < 2; ++bj)
; #pragma unroll
;                     for (int n = 0; n < 2; ++n) { const int tc = bj * 128 + wc * 32 + 8 * fq + 4 * n; f32x4 v = acc[ai][bj][m][n];
;                         if (pn < 2) { *(f32x4*)(XA + (size_t)row * 512 + pn * 256 + tc) = v; }
;                         else if (pn <= 4) {
;                             const bool isv = (pn == 4 && bj == 1);
;                             if (!isv && (wc & 1) == 0) {
;                                 const int tix = row < cfg::MP ? (row & 2047) : 2048 + (row & 3);
;                                 const f32x4 cs = *(const f32x4*)(ropec + tix * 8 + 4 * n), sn = *(const f32x4*)(ropes + tix * 8 + 4 * n);
; #pragma unroll
;                                 for (int i = 0; i < 4; ++i) { const float p = shx16(v[i], fq & 1); const float rv = v[i] * cs[i] + (fq == 0 ? -p : p) * sn[i]; v[i] = fq < 2 ? rv : v[i]; }
;                             }
;                             if (pn < 4) st_bf4(Q + (size_t)row * 512 + (pn - 2) * 256 + tc, v);
	v_mov_b32_e32 v50, v216
	v_mov_b32_e32 v73, v220
	v_pk_mul_f32 v[50:51], v[72:73], v[50:51]
	v_mov_b32_e32 v64, v41
	v_add_f32_e32 v44, v50, v51
	v_mov_b32_e32 v50, v41
	v_mov_b32_e32 v51, v41
	s_nop 1
	v_permlane16_swap_b32_e32 v50, v51
	v_cndmask_b32_e64 v50, v50, v51, s[6:7]
	v_cndmask_b32_e64 v51, v50, -v50, s[10:11]
	v_mov_b32_e32 v50, v217
	v_mov_b32_e32 v65, v221
	v_pk_mul_f32 v[50:51], v[64:65], v[50:51]
	v_mov_b32_e32 v64, v42
	v_add_f32_e32 v45, v50, v51
	v_mov_b32_e32 v50, v42
	v_mov_b32_e32 v51, v42
	s_nop 1
	v_permlane16_swap_b32_e32 v50, v51
	v_cndmask_b32_e64 v50, v50, v51, s[6:7]
	v_cndmask_b32_e64 v51, v50, -v50, s[10:11]
	v_mov_b32_e32 v65, v222
	v_mov_b32_e32 v50, v218
	v_pk_mul_f32 v[50:51], v[64:65], v[50:51]
	v_mov_b32_e32 v66, v43
	v_add_f32_e32 v46, v50, v51
	v_mov_b32_e32 v50, v43
	v_mov_b32_e32 v51, v43
	s_nop 1
	v_permlane16_swap_b32_e32 v50, v51
	v_cndmask_b32_e64 v50, v50, v51, s[6:7]
	v_cndmask_b32_e64 v51, v50, -v50, s[10:11]
	v_mov_b32_e32 v50, v219
	v_mov_b32_e32 v67, v223
	v_pk_mul_f32 v[50:51], v[66:67], v[50:51]
	v_cndmask_b32_e64 v44, v40, v44, s[8:9]
	v_add_f32_e32 v47, v50, v51
	v_cndmask_b32_e64 v45, v41, v45, s[8:9]
	v_cndmask_b32_e64 v46, v42, v46, s[8:9]
	v_cndmask_b32_e64 v47, v43, v47, s[8:9]
	v_mov_b32_e32 v66, v44
	v_mov_b32_e32 v71, v45
	v_mov_b32_e32 v67, v46
	v_mov_b32_e32 v72, v47
	v_lshl_add_u64 v[44:45], s[82:83], 0, v[52:53]
	v_lshl_add_u64 v[44:45], s[0:1], 1, v[44:45]
	v_lshlrev_b32_e32 v96, 1, v142
	v_lshl_add_u64 v[44:45], v[44:45], 0, v[96:97]
	v_cvt_pk_bf16_f32 v46, v66, v71
	v_cvt_pk_bf16_f32 v47, v67, v72
	global_store_dwordx2 v[44:45], v[46:47], off offset:-1016
	v_lshlrev_b32_e32 v46, 2, v70
	v_mov_b32_e32 v46, v36
	v_mov_b32_e32 v47, v36
	s_nop 1
	v_permlane16_swap_b32_e32 v46, v47
	v_cndmask_b32_e64 v46, v46, v47, s[6:7]
	v_cndmask_b32_e64 v47, v46, -v46, s[10:11]
	v_mov_b32_e32 v50, v36
	v_mov_b32_e32 v46, v208
	v_mov_b32_e32 v51, v212
	v_pk_mul_f32 v[46:47], v[50:51], v[46:47]
	v_mov_b32_e32 v60, v37
	v_add_f32_e32 v40, v46, v47
	v_mov_b32_e32 v46, v37
	v_mov_b32_e32 v47, v37
	s_nop 1
	v_permlane16_swap_b32_e32 v46, v47
	v_cndmask_b32_e64 v46, v46, v47, s[6:7]
	v_cndmask_b32_e64 v47, v46, -v46, s[10:11]
	v_mov_b32_e32 v46, v209
	v_mov_b32_e32 v61, v213
	v_pk_mul_f32 v[46:47], v[60:61], v[46:47]
	v_mov_b32_e32 v50, v38
	v_add_f32_e32 v41, v46, v47
	v_mov_b32_e32 v46, v38
	v_mov_b32_e32 v47, v38
	s_nop 1
	v_permlane16_swap_b32_e32 v46, v47
	v_cndmask_b32_e64 v46, v46, v47, s[6:7]
	v_cndmask_b32_e64 v47, v46, -v46, s[10:11]
	v_mov_b32_e32 v51, v214
	v_mov_b32_e32 v46, v210
	v_pk_mul_f32 v[46:47], v[50:51], v[46:47]
	v_mov_b32_e32 v62, v39
	v_add_f32_e32 v42, v46, v47
	v_mov_b32_e32 v46, v39
	v_mov_b32_e32 v47, v39
	s_nop 1
	v_permlane16_swap_b32_e32 v46, v47
	v_cndmask_b32_e64 v46, v46, v47, s[6:7]
	v_cndmask_b32_e64 v47, v46, -v46, s[10:11]
	v_mov_b32_e32 v46, v211
	v_mov_b32_e32 v63, v215
	v_pk_mul_f32 v[46:47], v[62:63], v[46:47]
	v_cndmask_b32_e64 v40, v36, v40, s[8:9]
	v_add_f32_e32 v43, v46, v47
	v_cndmask_b32_e64 v41, v37, v41, s[8:9]
	v_cndmask_b32_e64 v42, v38, v42, s[8:9]
	v_cndmask_b32_e64 v43, v39, v43, s[8:9]
	v_mov_b32_e32 v60, v40
	v_mov_b32_e32 v62, v41
	v_mov_b32_e32 v61, v42
	v_mov_b32_e32 v63, v43
	v_lshl_add_u64 v[40:41], s[82:83], 0, v[52:53]
	v_lshl_add_u64 v[40:41], s[0:1], 1, v[40:41]
	v_lshlrev_b32_e32 v96, 1, v142
	v_lshl_add_u64 v[40:41], v[40:41], 0, v[96:97]
	v_cvt_pk_bf16_f32 v42, v60, v62
	v_cvt_pk_bf16_f32 v43, v61, v63
	global_store_dwordx2 v[40:41], v[42:43], off offset:-768
	v_lshlrev_b32_e32 v40, 2, v70
	v_mov_b32_e32 v46, v32
	v_mov_b32_e32 v47, v32
	s_nop 1
	v_permlane16_swap_b32_e32 v46, v47
	v_cndmask_b32_e64 v46, v46, v47, s[6:7]
	v_cndmask_b32_e64 v47, v46, -v46, s[10:11]
	v_mov_b32_e32 v50, v32
	v_mov_b32_e32 v46, v216
	v_mov_b32_e32 v51, v220
	v_pk_mul_f32 v[46:47], v[50:51], v[46:47]
	v_mov_b32_e32 v40, v33
	v_add_f32_e32 v36, v46, v47
	v_mov_b32_e32 v46, v33
	s_nop 1
	v_permlane16_swap_b32_e32 v40, v46
	v_cndmask_b32_e64 v40, v40, v46, s[6:7]
	v_cndmask_b32_e64 v47, v40, -v40, s[10:11]
	v_mov_b32_e32 v40, v33
	v_mov_b32_e32 v46, v217
	v_mov_b32_e32 v41, v221
	v_pk_mul_f32 v[40:41], v[40:41], v[46:47]
	v_mov_b32_e32 v46, v34
	v_add_f32_e32 v37, v40, v41
	v_mov_b32_e32 v40, v34
	v_mov_b32_e32 v41, v34
	s_nop 1
	v_permlane16_swap_b32_e32 v40, v41
	v_cndmask_b32_e64 v40, v40, v41, s[6:7]
	v_cndmask_b32_e64 v41, v40, -v40, s[10:11]
	v_mov_b32_e32 v47, v222
	v_mov_b32_e32 v40, v218
	v_pk_mul_f32 v[40:41], v[46:47], v[40:41]
	v_mov_b32_e32 v42, v35
	v_add_f32_e32 v38, v40, v41
	v_mov_b32_e32 v40, v35
	v_mov_b32_e32 v41, v35
	s_nop 1
	v_permlane16_swap_b32_e32 v40, v41
	v_cndmask_b32_e64 v40, v40, v41, s[6:7]
	v_cndmask_b32_e64 v41, v40, -v40, s[10:11]
	v_mov_b32_e32 v40, v219
	v_mov_b32_e32 v43, v223
	v_pk_mul_f32 v[40:41], v[42:43], v[40:41]
	v_cndmask_b32_e64 v36, v32, v36, s[8:9]
	v_add_f32_e32 v39, v40, v41
	v_cndmask_b32_e64 v37, v33, v37, s[8:9]
	v_cndmask_b32_e64 v38, v34, v38, s[8:9]
	v_cndmask_b32_e64 v39, v35, v39, s[8:9]
	v_mov_b32_e32 v46, v36
	v_mov_b32_e32 v50, v37
	v_mov_b32_e32 v47, v38
	v_mov_b32_e32 v51, v39
	s_mov_b64 s[70:71], -1
	s_andn2_b64 vcc, exec, s[70:71]
	v_lshl_add_u64 v[36:37], s[82:83], 0, v[52:53]
	v_lshl_add_u64 v[36:37], s[0:1], 1, v[36:37]
	v_lshlrev_b32_e32 v96, 1, v142
	v_lshl_add_u64 v[36:37], v[36:37], 0, v[96:97]
	v_cvt_pk_bf16_f32 v38, v46, v50
	v_cvt_pk_bf16_f32 v39, v47, v51
	global_store_dwordx2 v[36:37], v[38:39], off offset:-760
	v_or_b32_e32 v32, 32, v68
	v_mad_i64_i32 v[42:43], s[18:19], v32, s61, 0
	s_movk_i32 s18, 0x7ef
	s_nop 0
	v_bitop3_b32 v34, v68, s18, 32 bitop3:0xc8
	s_movk_i32 s18, 0x4000
	v_cmp_gt_i32_e32 vcc, s18, v32
	v_ashrrev_i32_e32 v33, 31, v32
	s_nop 0
	v_cndmask_b32_e32 v35, v151, v34, vcc
	v_lshlrev_b32_e32 v53, 3, v35
	v_add_u32_e32 v35, 0xffffc020, v68
	v_lshrrev_b32_e32 v52, 2, v35
	v_lshlrev_b64 v[36:37], 10, v[32:33]
	v_lshlrev_b32_e32 v48, 2, v53
	global_load_dwordx4 v[208:211], v48, s[44:45]
	global_load_dwordx4 v[212:215], v48, s[4:5]
	global_load_dwordx4 v[216:219], v48, s[44:45] offset:16
	global_load_dwordx4 v[220:223], v48, s[4:5] offset:16
	v_mov_b32_e32 v54, v28
	v_mov_b32_e32 v55, v28
	s_nop 1
	v_permlane16_swap_b32_e32 v54, v55
	v_cndmask_b32_e64 v54, v54, v55, s[6:7]
	v_cndmask_b32_e64 v55, v54, -v54, s[10:11]
	v_mov_b32_e32 v56, v28
	s_waitcnt vmcnt(2)
; __device__ __forceinline__ float shx16(float v, int odd  ) { const unsigned x = __builtin_bit_cast(unsigned, v); auto r = __builtin_amdgcn_permlane16_swap(x, x, false, false); return __builtin_bit_cast(float, odd ? r[0] : r[1]); }
; __device__ __forceinline__ void st_bf4(bf16_t* p, const f32x4 v) { u32x2 w; w.x = cvt_pk_bf16(v[0], v[1]); w.y = cvt_pk_bf16(v[2], v[3]); *(u32x2*)p = w; }
;     __device__ __forceinline__ void operator()(const f32x4 (&acc)[2][2][4][2], const Unit& u, int wr, int wc, int fr, int fq) const {
;     ...
;             for (int m = 0; m < 4; ++m) { const int row = u.pm * 256 + ai * 128 + wr * 64 + m * 16 + fr;
; #pragma unroll
;                 for (int bj = 0; bj < 2; ++bj)
; #pragma unroll
;                     for (int n = 0; n < 2; ++n) { const int tc = bj * 128 + wc * 32 + 8 * fq + 4 * n; f32x4 v = acc[ai][bj][m][n];
;                         if (pn < 2) { *(f32x4*)(XA + (size_t)row * 512 + pn * 256 + tc) = v; }
;                         else if (pn <= 4) {
;                             const bool isv = (pn == 4 && bj == 1);
;                             if (!isv && (wc & 1) == 0) {
;                                 const int tix = row < cfg::MP ? (row & 2047) : 2048 + (row & 3);
;                                 const f32x4 cs = *(const f32x4*)(ropec + tix * 8 + 4 * n), sn = *(const f32x4*)(ropes + tix * 8 + 4 * n);
; #pragma unroll
;                                 for (int i = 0; i < 4; ++i) { const float p = shx16(v[i], fq & 1); const float rv = v[i] * cs[i] + (fq == 0 ? -p : p) * sn[i]; v[i] = fq < 2 ? rv : v[i]; }
;                             }
;                             if (pn < 4) st_bf4(Q + (size_t)row * 512 + (pn - 2) * 256 + tc, v);
	v_mov_b32_e32 v54, v208
	v_mov_b32_e32 v57, v212
	v_pk_mul_f32 v[54:55], v[56:57], v[54:55]
	v_mov_b32_e32 v48, v29
	v_add_f32_e32 v32, v54, v55
	v_mov_b32_e32 v54, v29
	s_nop 1
	v_permlane16_swap_b32_e32 v48, v54
	v_cndmask_b32_e64 v48, v48, v54, s[6:7]
	v_cndmask_b32_e64 v55, v48, -v48, s[10:11]
	v_mov_b32_e32 v48, v29
	v_mov_b32_e32 v54, v209
	v_mov_b32_e32 v49, v213
	v_pk_mul_f32 v[48:49], v[48:49], v[54:55]
	v_mov_b32_e32 v54, v30
	v_add_f32_e32 v33, v48, v49
	v_mov_b32_e32 v48, v30
	v_mov_b32_e32 v49, v30
	s_nop 1
	v_permlane16_swap_b32_e32 v48, v49
	v_cndmask_b32_e64 v48, v48, v49, s[6:7]
	v_cndmask_b32_e64 v49, v48, -v48, s[10:11]
	v_mov_b32_e32 v55, v214
	v_mov_b32_e32 v48, v210
	v_pk_mul_f32 v[48:49], v[54:55], v[48:49]
	v_mov_b32_e32 v50, v31
	v_add_f32_e32 v34, v48, v49
	v_mov_b32_e32 v48, v31
	v_mov_b32_e32 v49, v31
	s_nop 1
	v_permlane16_swap_b32_e32 v48, v49
	v_cndmask_b32_e64 v48, v48, v49, s[6:7]
	v_cndmask_b32_e64 v49, v48, -v48, s[10:11]
	v_mov_b32_e32 v48, v211
	v_mov_b32_e32 v51, v215
	v_pk_mul_f32 v[48:49], v[50:51], v[48:49]
	v_cndmask_b32_e64 v32, v28, v32, s[8:9]
	v_add_f32_e32 v35, v48, v49
	v_cndmask_b32_e64 v33, v29, v33, s[8:9]
	v_cndmask_b32_e64 v34, v30, v34, s[8:9]
	v_cndmask_b32_e64 v35, v31, v35, s[8:9]
	v_mov_b32_e32 v54, v32
	v_mov_b32_e32 v56, v33
	v_mov_b32_e32 v55, v34
	v_mov_b32_e32 v57, v35
	v_lshl_add_u64 v[32:33], s[82:83], 0, v[36:37]
	v_lshl_add_u64 v[32:33], s[0:1], 1, v[32:33]
	v_lshlrev_b32_e32 v96, 1, v142
	v_lshl_add_u64 v[32:33], v[32:33], 0, v[96:97]
	v_cvt_pk_bf16_f32 v34, v54, v56
	v_cvt_pk_bf16_f32 v35, v55, v57
	global_store_dwordx2 v[32:33], v[34:35], off offset:-1024
	v_lshlrev_b32_e32 v34, 2, v53
	v_mov_b32_e32 v34, v24
	v_mov_b32_e32 v35, v24
	s_nop 1
	v_permlane16_swap_b32_e32 v34, v35
	v_cndmask_b32_e64 v34, v34, v35, s[6:7]
	v_cndmask_b32_e64 v35, v34, -v34, s[10:11]
	v_mov_b32_e32 v54, v24
	s_waitcnt vmcnt(1)
	v_mov_b32_e32 v34, v216
	v_mov_b32_e32 v55, v220
	v_pk_mul_f32 v[34:35], v[54:55], v[34:35]
	v_mov_b32_e32 v48, v25
	v_add_f32_e32 v28, v34, v35
	v_mov_b32_e32 v34, v25
	v_mov_b32_e32 v35, v25
	s_nop 1
	v_permlane16_swap_b32_e32 v34, v35
	v_cndmask_b32_e64 v34, v34, v35, s[6:7]
	v_cndmask_b32_e64 v35, v34, -v34, s[10:11]
	v_mov_b32_e32 v34, v217
	v_mov_b32_e32 v49, v221
	v_pk_mul_f32 v[34:35], v[48:49], v[34:35]
	v_mov_b32_e32 v48, v26
	v_add_f32_e32 v29, v34, v35
	v_mov_b32_e32 v34, v26
	v_mov_b32_e32 v35, v26
	s_nop 1
	v_permlane16_swap_b32_e32 v34, v35
	v_cndmask_b32_e64 v34, v34, v35, s[6:7]
	v_cndmask_b32_e64 v35, v34, -v34, s[10:11]
	v_mov_b32_e32 v49, v222
	v_mov_b32_e32 v34, v218
	v_pk_mul_f32 v[34:35], v[48:49], v[34:35]
	v_mov_b32_e32 v50, v27
	v_add_f32_e32 v30, v34, v35
	v_mov_b32_e32 v34, v27
	v_mov_b32_e32 v35, v27
	s_nop 1
	v_permlane16_swap_b32_e32 v34, v35
	v_cndmask_b32_e64 v34, v34, v35, s[6:7]
	v_cndmask_b32_e64 v35, v34, -v34, s[10:11]
	v_mov_b32_e32 v34, v219
	v_mov_b32_e32 v51, v223
	v_pk_mul_f32 v[34:35], v[50:51], v[34:35]
	v_cndmask_b32_e64 v28, v24, v28, s[8:9]
	v_add_f32_e32 v31, v34, v35
	v_cndmask_b32_e64 v29, v25, v29, s[8:9]
	v_cndmask_b32_e64 v30, v26, v30, s[8:9]
	v_cndmask_b32_e64 v31, v27, v31, s[8:9]
	v_mov_b32_e32 v50, v28
	v_mov_b32_e32 v54, v29
	v_mov_b32_e32 v51, v30
	v_mov_b32_e32 v55, v31
	v_lshl_add_u64 v[28:29], s[82:83], 0, v[36:37]
	v_lshl_add_u64 v[28:29], s[0:1], 1, v[28:29]
	v_lshlrev_b32_e32 v96, 1, v142
	v_lshl_add_u64 v[28:29], v[28:29], 0, v[96:97]
	v_cvt_pk_bf16_f32 v30, v50, v54
	v_cvt_pk_bf16_f32 v31, v51, v55
	global_store_dwordx2 v[28:29], v[30:31], off offset:-1016
	v_lshlrev_b32_e32 v30, 2, v53
	v_mov_b32_e32 v30, v20
	v_mov_b32_e32 v31, v20
	s_nop 1
	v_permlane16_swap_b32_e32 v30, v31
	v_cndmask_b32_e64 v30, v30, v31, s[6:7]
	v_cndmask_b32_e64 v31, v30, -v30, s[10:11]
	v_mov_b32_e32 v34, v20
	v_mov_b32_e32 v30, v208
	v_mov_b32_e32 v35, v212
	v_pk_mul_f32 v[30:31], v[34:35], v[30:31]
	v_mov_b32_e32 v44, v21
	v_add_f32_e32 v24, v30, v31
	v_mov_b32_e32 v30, v21
	v_mov_b32_e32 v31, v21
	s_nop 1
	v_permlane16_swap_b32_e32 v30, v31
	v_cndmask_b32_e64 v30, v30, v31, s[6:7]
	v_cndmask_b32_e64 v31, v30, -v30, s[10:11]
	v_mov_b32_e32 v30, v209
	v_mov_b32_e32 v45, v213
	v_pk_mul_f32 v[30:31], v[44:45], v[30:31]
	v_mov_b32_e32 v34, v22
	v_add_f32_e32 v25, v30, v31
	v_mov_b32_e32 v30, v22
	v_mov_b32_e32 v31, v22
	s_nop 1
	v_permlane16_swap_b32_e32 v30, v31
	v_cndmask_b32_e64 v30, v30, v31, s[6:7]
	v_cndmask_b32_e64 v31, v30, -v30, s[10:11]
	v_mov_b32_e32 v35, v214
	v_mov_b32_e32 v30, v210
	v_pk_mul_f32 v[30:31], v[34:35], v[30:31]
	v_mov_b32_e32 v46, v23
	v_add_f32_e32 v26, v30, v31
	v_mov_b32_e32 v30, v23
	v_mov_b32_e32 v31, v23
	s_nop 1
	v_permlane16_swap_b32_e32 v30, v31
	v_cndmask_b32_e64 v30, v30, v31, s[6:7]
	v_cndmask_b32_e64 v31, v30, -v30, s[10:11]
	v_mov_b32_e32 v30, v211
	v_mov_b32_e32 v47, v215
	v_pk_mul_f32 v[30:31], v[46:47], v[30:31]
	v_cndmask_b32_e64 v24, v20, v24, s[8:9]
	v_add_f32_e32 v27, v30, v31
	v_cndmask_b32_e64 v25, v21, v25, s[8:9]
	v_cndmask_b32_e64 v26, v22, v26, s[8:9]
	v_cndmask_b32_e64 v27, v23, v27, s[8:9]
	v_mov_b32_e32 v44, v24
	v_mov_b32_e32 v46, v25
	v_mov_b32_e32 v45, v26
	v_mov_b32_e32 v47, v27
	v_lshl_add_u64 v[24:25], s[82:83], 0, v[36:37]
	v_lshl_add_u64 v[24:25], s[0:1], 1, v[24:25]
	v_lshlrev_b32_e32 v96, 1, v142
	v_lshl_add_u64 v[24:25], v[24:25], 0, v[96:97]
	v_cvt_pk_bf16_f32 v26, v44, v46
	v_cvt_pk_bf16_f32 v27, v45, v47
	global_store_dwordx2 v[24:25], v[26:27], off offset:-768
	v_lshlrev_b32_e32 v24, 2, v53
	v_mov_b32_e32 v30, v16
	v_mov_b32_e32 v31, v16
	s_nop 1
	v_permlane16_swap_b32_e32 v30, v31
	v_cndmask_b32_e64 v30, v30, v31, s[6:7]
	v_cndmask_b32_e64 v31, v30, -v30, s[10:11]
; __device__ __forceinline__ float shx16(float v, int odd  ) { const unsigned x = __builtin_bit_cast(unsigned, v); auto r = __builtin_amdgcn_permlane16_swap(x, x, false, false); return __builtin_bit_cast(float, odd ? r[0] : r[1]); }
; __device__ __forceinline__ void st_bf4(bf16_t* p, const f32x4 v) { u32x2 w; w.x = cvt_pk_bf16(v[0], v[1]); w.y = cvt_pk_bf16(v[2], v[3]); *(u32x2*)p = w; }
;     __device__ __forceinline__ void operator()(const f32x4 (&acc)[2][2][4][2], const Unit& u, int wr, int wc, int fr, int fq) const {
;     ...
;             for (int m = 0; m < 4; ++m) { const int row = u.pm * 256 + ai * 128 + wr * 64 + m * 16 + fr;
; #pragma unroll
;                 for (int bj = 0; bj < 2; ++bj)
; #pragma unroll
;                     for (int n = 0; n < 2; ++n) { const int tc = bj * 128 + wc * 32 + 8 * fq + 4 * n; f32x4 v = acc[ai][bj][m][n];
;                         if (pn < 2) { *(f32x4*)(XA + (size_t)row * 512 + pn * 256 + tc) = v; }
;                         else if (pn <= 4) {
;                             const bool isv = (pn == 4 && bj == 1);
;                             if (!isv && (wc & 1) == 0) {
;                                 const int tix = row < cfg::MP ? (row & 2047) : 2048 + (row & 3);
;                                 const f32x4 cs = *(const f32x4*)(ropec + tix * 8 + 4 * n), sn = *(const f32x4*)(ropes + tix * 8 + 4 * n);
; #pragma unroll
;                                 for (int i = 0; i < 4; ++i) { const float p = shx16(v[i], fq & 1); const float rv = v[i] * cs[i] + (fq == 0 ? -p : p) * sn[i]; v[i] = fq < 2 ? rv : v[i]; }
;                             }
;                             if (pn < 4) st_bf4(Q + (size_t)row * 512 + (pn - 2) * 256 + tc, v);
	v_mov_b32_e32 v34, v16
	v_mov_b32_e32 v30, v216
	v_mov_b32_e32 v35, v220
	v_pk_mul_f32 v[30:31], v[34:35], v[30:31]
	v_mov_b32_e32 v24, v17
	v_add_f32_e32 v20, v30, v31
	v_mov_b32_e32 v30, v17
	s_nop 1
	v_permlane16_swap_b32_e32 v24, v30
	v_cndmask_b32_e64 v24, v24, v30, s[6:7]
	v_cndmask_b32_e64 v31, v24, -v24, s[10:11]
	v_mov_b32_e32 v24, v17
	v_mov_b32_e32 v30, v217
	v_mov_b32_e32 v25, v221
	v_pk_mul_f32 v[24:25], v[24:25], v[30:31]
	v_mov_b32_e32 v30, v18
	v_add_f32_e32 v21, v24, v25
	v_mov_b32_e32 v24, v18
	v_mov_b32_e32 v25, v18
	s_nop 1
	v_permlane16_swap_b32_e32 v24, v25
	v_cndmask_b32_e64 v24, v24, v25, s[6:7]
	v_cndmask_b32_e64 v25, v24, -v24, s[10:11]
	v_mov_b32_e32 v31, v222
	v_mov_b32_e32 v24, v218
	v_pk_mul_f32 v[24:25], v[30:31], v[24:25]
	v_mov_b32_e32 v26, v19
	v_add_f32_e32 v22, v24, v25
	v_mov_b32_e32 v24, v19
	v_mov_b32_e32 v25, v19
	s_nop 1
	v_permlane16_swap_b32_e32 v24, v25
	v_cndmask_b32_e64 v24, v24, v25, s[6:7]
	v_cndmask_b32_e64 v25, v24, -v24, s[10:11]
	v_mov_b32_e32 v24, v219
	v_mov_b32_e32 v27, v223
	v_pk_mul_f32 v[24:25], v[26:27], v[24:25]
	v_cndmask_b32_e64 v20, v16, v20, s[8:9]
	v_add_f32_e32 v23, v24, v25
	v_cndmask_b32_e64 v21, v17, v21, s[8:9]
	v_cndmask_b32_e64 v22, v18, v22, s[8:9]
	v_cndmask_b32_e64 v23, v19, v23, s[8:9]
	v_mov_b32_e32 v30, v20
	v_mov_b32_e32 v34, v21
	v_mov_b32_e32 v31, v22
	v_mov_b32_e32 v35, v23
	s_mov_b64 s[70:71], -1
	s_andn2_b64 vcc, exec, s[70:71]
	v_lshl_add_u64 v[20:21], s[82:83], 0, v[36:37]
	v_lshl_add_u64 v[20:21], s[0:1], 1, v[20:21]
	v_lshlrev_b32_e32 v96, 1, v142
	v_lshl_add_u64 v[20:21], v[20:21], 0, v[96:97]
	v_cvt_pk_bf16_f32 v22, v30, v34
	v_cvt_pk_bf16_f32 v23, v31, v35
	global_store_dwordx2 v[20:21], v[22:23], off offset:-760
	v_or_b32_e32 v16, 48, v68
	v_mad_i64_i32 v[26:27], s[18:19], v16, s61, 0
	s_movk_i32 s18, 0x3fff
	s_nop 0
	v_cmp_lt_i32_e64 s[20:21], s18, v16
	s_movk_i32 s18, 0x7ff
	v_bitop3_b32 v18, v68, s18, 48 bitop3:0xc8
	s_movk_i32 s18, 0x4000
	v_cmp_gt_i32_e32 vcc, s18, v16
	v_add_u32_e32 v96, 0xfffff880, v18
	v_ashrrev_i32_e32 v17, 31, v16
	v_cndmask_b32_e32 v19, v151, v18, vcc
	v_lshlrev_b32_e32 v37, 3, v19
	v_add_u32_e32 v19, 0xffffc030, v68
	v_lshlrev_b64 v[28:29], 7, v[96:97]
	v_lshlrev_b64 v[24:25], 11, v[16:17]
	v_lshlrev_b64 v[22:23], 8, v[16:17]
	v_lshrrev_b32_e32 v36, 2, v19
	v_lshlrev_b64 v[20:21], 10, v[16:17]
	v_lshlrev_b32_e32 v32, 2, v37
	global_load_dwordx4 v[208:211], v32, s[44:45]
	global_load_dwordx4 v[212:215], v32, s[4:5]
	global_load_dwordx4 v[216:219], v32, s[44:45] offset:16
	global_load_dwordx4 v[220:223], v32, s[4:5] offset:16
	v_mov_b32_e32 v38, v12
	v_mov_b32_e32 v39, v12
	s_nop 1
	v_permlane16_swap_b32_e32 v38, v39
	v_cndmask_b32_e64 v38, v38, v39, s[6:7]
	v_cndmask_b32_e64 v39, v38, -v38, s[10:11]
	v_mov_b32_e32 v40, v12
	s_waitcnt vmcnt(2)
	v_mov_b32_e32 v38, v208
	v_mov_b32_e32 v41, v212
	v_pk_mul_f32 v[38:39], v[40:41], v[38:39]
	v_mov_b32_e32 v32, v13
	v_add_f32_e32 v16, v38, v39
	v_mov_b32_e32 v38, v13
	s_nop 1
	v_permlane16_swap_b32_e32 v32, v38
	v_cndmask_b32_e64 v32, v32, v38, s[6:7]
	v_cndmask_b32_e64 v39, v32, -v32, s[10:11]
	v_mov_b32_e32 v32, v13
	v_mov_b32_e32 v38, v209
	v_mov_b32_e32 v33, v213
	v_pk_mul_f32 v[32:33], v[32:33], v[38:39]
	v_mov_b32_e32 v38, v14
	v_add_f32_e32 v17, v32, v33
	v_mov_b32_e32 v32, v14
	v_mov_b32_e32 v33, v14
	s_nop 1
	v_permlane16_swap_b32_e32 v32, v33
	v_cndmask_b32_e64 v32, v32, v33, s[6:7]
	v_cndmask_b32_e64 v33, v32, -v32, s[10:11]
	v_mov_b32_e32 v39, v214
	v_mov_b32_e32 v32, v210
	v_pk_mul_f32 v[32:33], v[38:39], v[32:33]
	v_mov_b32_e32 v34, v15
	v_add_f32_e32 v18, v32, v33
	v_mov_b32_e32 v32, v15
	v_mov_b32_e32 v33, v15
	s_nop 1
	v_permlane16_swap_b32_e32 v32, v33
	v_cndmask_b32_e64 v32, v32, v33, s[6:7]
	v_cndmask_b32_e64 v33, v32, -v32, s[10:11]
	v_mov_b32_e32 v32, v211
	v_mov_b32_e32 v35, v215
	v_pk_mul_f32 v[32:33], v[34:35], v[32:33]
	v_cndmask_b32_e64 v16, v12, v16, s[8:9]
	v_add_f32_e32 v19, v32, v33
	v_cndmask_b32_e64 v17, v13, v17, s[8:9]
	v_cndmask_b32_e64 v18, v14, v18, s[8:9]
	v_cndmask_b32_e64 v19, v15, v19, s[8:9]
	v_mov_b32_e32 v38, v16
	v_mov_b32_e32 v40, v17
	v_mov_b32_e32 v39, v18
	v_mov_b32_e32 v41, v19
	v_lshl_add_u64 v[16:17], s[82:83], 0, v[20:21]
	v_lshl_add_u64 v[16:17], s[0:1], 1, v[16:17]
	v_lshlrev_b32_e32 v96, 1, v142
	v_lshl_add_u64 v[16:17], v[16:17], 0, v[96:97]
	v_cvt_pk_bf16_f32 v18, v38, v40
	v_cvt_pk_bf16_f32 v19, v39, v41
	global_store_dwordx2 v[16:17], v[18:19], off offset:-1024
	v_lshl_add_u64 v[16:17], s[30:31], 0, v[24:25]
	v_lshl_add_u64 v[16:17], s[92:93], 2, v[16:17]
	v_lshlrev_b32_e32 v18, 2, v37
	v_mov_b32_e32 v18, v8
	v_mov_b32_e32 v19, v8
	s_nop 1
	v_permlane16_swap_b32_e32 v18, v19
	v_cndmask_b32_e64 v18, v18, v19, s[6:7]
	v_cndmask_b32_e64 v19, v18, -v18, s[10:11]
	v_mov_b32_e32 v38, v8
	s_waitcnt vmcnt(1)
; __device__ __forceinline__ float shx16(float v, int odd  ) { const unsigned x = __builtin_bit_cast(unsigned, v); auto r = __builtin_amdgcn_permlane16_swap(x, x, false, false); return __builtin_bit_cast(float, odd ? r[0] : r[1]); }
; __device__ __forceinline__ void st_bf4(bf16_t* p, const f32x4 v) { u32x2 w; w.x = cvt_pk_bf16(v[0], v[1]); w.y = cvt_pk_bf16(v[2], v[3]); *(u32x2*)p = w; }
;     __device__ __forceinline__ void operator()(const f32x4 (&acc)[2][2][4][2], const Unit& u, int wr, int wc, int fr, int fq) const {
;     ...
;             for (int m = 0; m < 4; ++m) { const int row = u.pm * 256 + ai * 128 + wr * 64 + m * 16 + fr;
; #pragma unroll
;                 for (int bj = 0; bj < 2; ++bj)
; #pragma unroll
;                     for (int n = 0; n < 2; ++n) { const int tc = bj * 128 + wc * 32 + 8 * fq + 4 * n; f32x4 v = acc[ai][bj][m][n];
;                         if (pn < 2) { *(f32x4*)(XA + (size_t)row * 512 + pn * 256 + tc) = v; }
;                         else if (pn <= 4) {
;                             const bool isv = (pn == 4 && bj == 1);
;                             if (!isv && (wc & 1) == 0) {
;                                 const int tix = row < cfg::MP ? (row & 2047) : 2048 + (row & 3);
;                                 const f32x4 cs = *(const f32x4*)(ropec + tix * 8 + 4 * n), sn = *(const f32x4*)(ropes + tix * 8 + 4 * n);
; #pragma unroll
;                                 for (int i = 0; i < 4; ++i) { const float p = shx16(v[i], fq & 1); const float rv = v[i] * cs[i] + (fq == 0 ? -p : p) * sn[i]; v[i] = fq < 2 ? rv : v[i]; }
;                             }
;                             if (pn < 4) st_bf4(Q + (size_t)row * 512 + (pn - 2) * 256 + tc, v);
	v_mov_b32_e32 v18, v216
	v_mov_b32_e32 v39, v220
	v_pk_mul_f32 v[18:19], v[38:39], v[18:19]
	v_mov_b32_e32 v32, v9
	v_add_f32_e32 v12, v18, v19
	v_mov_b32_e32 v18, v9
	v_mov_b32_e32 v19, v9
	s_nop 1
	v_permlane16_swap_b32_e32 v18, v19
	v_cndmask_b32_e64 v18, v18, v19, s[6:7]
	v_cndmask_b32_e64 v19, v18, -v18, s[10:11]
	v_mov_b32_e32 v18, v217
	v_mov_b32_e32 v33, v221
	v_pk_mul_f32 v[18:19], v[32:33], v[18:19]
	v_mov_b32_e32 v32, v10
	v_add_f32_e32 v13, v18, v19
	v_mov_b32_e32 v18, v10
	v_mov_b32_e32 v19, v10
	s_nop 1
	v_permlane16_swap_b32_e32 v18, v19
	v_cndmask_b32_e64 v18, v18, v19, s[6:7]
	v_cndmask_b32_e64 v19, v18, -v18, s[10:11]
	v_mov_b32_e32 v33, v222
	v_mov_b32_e32 v18, v218
	v_pk_mul_f32 v[18:19], v[32:33], v[18:19]
	v_mov_b32_e32 v34, v11
	v_add_f32_e32 v14, v18, v19
	v_mov_b32_e32 v18, v11
	v_mov_b32_e32 v19, v11
	s_nop 1
	v_permlane16_swap_b32_e32 v18, v19
	v_cndmask_b32_e64 v18, v18, v19, s[6:7]
	v_cndmask_b32_e64 v19, v18, -v18, s[10:11]
	v_mov_b32_e32 v18, v219
	v_mov_b32_e32 v35, v223
	v_pk_mul_f32 v[18:19], v[34:35], v[18:19]
	v_cndmask_b32_e64 v12, v8, v12, s[8:9]
	v_add_f32_e32 v15, v18, v19
	v_cndmask_b32_e64 v13, v9, v13, s[8:9]
	v_cndmask_b32_e64 v14, v10, v14, s[8:9]
	v_cndmask_b32_e64 v15, v11, v15, s[8:9]
	v_mov_b32_e32 v34, v12
	v_mov_b32_e32 v38, v13
	v_mov_b32_e32 v35, v14
	v_mov_b32_e32 v39, v15
	v_lshl_add_u64 v[12:13], s[82:83], 0, v[20:21]
	v_lshl_add_u64 v[12:13], s[0:1], 1, v[12:13]
	v_lshlrev_b32_e32 v96, 1, v142
	v_lshl_add_u64 v[12:13], v[12:13], 0, v[96:97]
	v_cvt_pk_bf16_f32 v14, v34, v38
	v_cvt_pk_bf16_f32 v15, v35, v39
	global_store_dwordx2 v[12:13], v[14:15], off offset:-1016
	s_mov_b64 s[70:71], 0x1100000
	v_lshl_add_u64 v[12:13], v[28:29], 0, s[70:71]
	v_lshlrev_b32_e32 v14, 2, v37
	v_mov_b32_e32 v14, v4
	v_mov_b32_e32 v15, v4
	s_nop 1
	v_permlane16_swap_b32_e32 v14, v15
	v_cndmask_b32_e64 v14, v14, v15, s[6:7]
	v_cndmask_b32_e64 v15, v14, -v14, s[10:11]
	v_mov_b32_e32 v18, v4
	v_mov_b32_e32 v14, v208
	v_mov_b32_e32 v19, v212
	v_pk_mul_f32 v[14:15], v[18:19], v[14:15]
	v_mov_b32_e32 v28, v5
	v_add_f32_e32 v8, v14, v15
	v_mov_b32_e32 v14, v5
	v_mov_b32_e32 v15, v5
	s_nop 1
	v_permlane16_swap_b32_e32 v14, v15
	v_cndmask_b32_e64 v14, v14, v15, s[6:7]
	v_cndmask_b32_e64 v15, v14, -v14, s[10:11]
	v_mov_b32_e32 v14, v209
	v_mov_b32_e32 v29, v213
	v_pk_mul_f32 v[14:15], v[28:29], v[14:15]
	v_mov_b32_e32 v18, v6
	v_add_f32_e32 v9, v14, v15
	v_mov_b32_e32 v14, v6
	v_mov_b32_e32 v15, v6
	s_nop 1
	v_permlane16_swap_b32_e32 v14, v15
	v_cndmask_b32_e64 v14, v14, v15, s[6:7]
	v_cndmask_b32_e64 v15, v14, -v14, s[10:11]
	v_mov_b32_e32 v19, v214
	v_mov_b32_e32 v14, v210
	v_pk_mul_f32 v[14:15], v[18:19], v[14:15]
	v_mov_b32_e32 v30, v7
	v_add_f32_e32 v10, v14, v15
	v_mov_b32_e32 v14, v7
	v_mov_b32_e32 v15, v7
	s_nop 1
	v_permlane16_swap_b32_e32 v14, v15
	v_cndmask_b32_e64 v14, v14, v15, s[6:7]
	v_cndmask_b32_e64 v15, v14, -v14, s[10:11]
	v_mov_b32_e32 v14, v211
	v_mov_b32_e32 v31, v215
	v_pk_mul_f32 v[14:15], v[30:31], v[14:15]
	v_cndmask_b32_e64 v8, v4, v8, s[8:9]
	v_add_f32_e32 v11, v14, v15
	v_cndmask_b32_e64 v9, v5, v9, s[8:9]
	v_cndmask_b32_e64 v10, v6, v10, s[8:9]
	v_cndmask_b32_e64 v11, v7, v11, s[8:9]
	v_mov_b32_e32 v28, v8
	v_mov_b32_e32 v30, v9
	v_mov_b32_e32 v29, v10
	v_mov_b32_e32 v31, v11
	v_lshl_add_u64 v[8:9], s[82:83], 0, v[20:21]
	v_lshl_add_u64 v[8:9], s[0:1], 1, v[8:9]
	v_lshlrev_b32_e32 v96, 1, v142
	v_lshl_add_u64 v[8:9], v[8:9], 0, v[96:97]
	v_cvt_pk_bf16_f32 v10, v28, v30
	v_cvt_pk_bf16_f32 v11, v29, v31
	global_store_dwordx2 v[8:9], v[10:11], off offset:-768
	s_mov_b32 s70, 0x1200000
	s_mov_b32 s71, 0x1400000
	v_lshlrev_b32_e32 v8, 2, v37
	v_mov_b32_e32 v14, v0
	v_mov_b32_e32 v15, v0
	s_nop 1
	v_permlane16_swap_b32_e32 v14, v15
	v_cndmask_b32_e64 v14, v14, v15, s[6:7]
	v_cndmask_b32_e64 v15, v14, -v14, s[10:11]
	v_mov_b32_e32 v18, v0
	v_mov_b32_e32 v14, v216
	v_mov_b32_e32 v19, v220
	v_pk_mul_f32 v[14:15], v[18:19], v[14:15]
	v_mov_b32_e32 v8, v1
	v_add_f32_e32 v4, v14, v15
	v_mov_b32_e32 v14, v1
	s_nop 1
	v_permlane16_swap_b32_e32 v8, v14
	v_cndmask_b32_e64 v8, v8, v14, s[6:7]
	v_cndmask_b32_e64 v15, v8, -v8, s[10:11]
	v_mov_b32_e32 v8, v1
	v_mov_b32_e32 v14, v217
	v_mov_b32_e32 v9, v221
	v_pk_mul_f32 v[8:9], v[8:9], v[14:15]
	v_mov_b32_e32 v14, v2
	v_add_f32_e32 v5, v8, v9
	v_mov_b32_e32 v8, v2
	v_mov_b32_e32 v9, v2
	s_nop 1
	v_permlane16_swap_b32_e32 v8, v9
	v_cndmask_b32_e64 v8, v8, v9, s[6:7]
	v_cndmask_b32_e64 v9, v8, -v8, s[10:11]
	v_mov_b32_e32 v15, v222
	v_mov_b32_e32 v8, v218
	v_pk_mul_f32 v[8:9], v[14:15], v[8:9]
	v_mov_b32_e32 v10, v3
	v_add_f32_e32 v6, v8, v9
	v_mov_b32_e32 v8, v3
	v_mov_b32_e32 v9, v3
	s_nop 1
	v_permlane16_swap_b32_e32 v8, v9
	v_cndmask_b32_e64 v8, v8, v9, s[6:7]
	v_cndmask_b32_e64 v9, v8, -v8, s[10:11]
	v_mov_b32_e32 v8, v219
	v_mov_b32_e32 v11, v223
	v_pk_mul_f32 v[8:9], v[10:11], v[8:9]
	v_cndmask_b32_e64 v4, v0, v4, s[8:9]
	v_add_f32_e32 v7, v8, v9
	v_cndmask_b32_e64 v5, v1, v5, s[8:9]
	v_cndmask_b32_e64 v6, v2, v6, s[8:9]
	v_cndmask_b32_e64 v7, v3, v7, s[8:9]
	v_mov_b32_e32 v14, v4
	v_mov_b32_e32 v18, v5
	v_mov_b32_e32 v15, v6
	v_mov_b32_e32 v19, v7
	s_mov_b64 s[14:15], -1
	v_lshl_add_u64 v[4:5], s[82:83], 0, v[20:21]
	v_lshl_add_u64 v[4:5], s[0:1], 1, v[4:5]
	v_lshlrev_b32_e32 v96, 1, v142
	v_lshl_add_u64 v[4:5], v[4:5], 0, v[96:97]
	v_cvt_pk_bf16_f32 v6, v14, v18
	v_cvt_pk_bf16_f32 v7, v15, v19
	global_store_dwordx2 v[4:5], v[6:7], off offset:-760
	s_branch .LBB0_1574
; __device__ __forceinline__ float shx16(float v, int odd  ) { const unsigned x = __builtin_bit_cast(unsigned, v); auto r = __builtin_amdgcn_permlane16_swap(x, x, false, false); return __builtin_bit_cast(float, odd ? r[0] : r[1]); }
; __device__ __forceinline__ unsigned cvt_pk_bf16(float lo, float hi) { unsigned r; asm volatile("v_cvt_pk_bf16_f32 %0, %1, %2" : "=v"(r) : "v"(lo), "v"(hi)); return r; }
; __device__ __forceinline__ void st_bf4(bf16_t* p, const f32x4 v) { u32x2 w; w.x = cvt_pk_bf16(v[0], v[1]); w.y = cvt_pk_bf16(v[2], v[3]); *(u32x2*)p = w; }
;     __device__ __forceinline__ void operator()(const f32x4 (&acc)[2][2][4][2], const Unit& u, int wr, int wc, int fr, int fq) const {
;     ...
;             for (int m = 0; m < 4; ++m) { const int row = u.pm * 256 + ai * 128 + wr * 64 + m * 16 + fr;
; #pragma unroll
;                 for (int bj = 0; bj < 2; ++bj)
; #pragma unroll
;                     for (int n = 0; n < 2; ++n) { const int tc = bj * 128 + wc * 32 + 8 * fq + 4 * n; f32x4 v = acc[ai][bj][m][n];
;                         if (pn < 2) { *(f32x4*)(XA + (size_t)row * 512 + pn * 256 + tc) = v; }
;                         else if (pn <= 4) {
;                             const bool isv = (pn == 4 && bj == 1);
;                             if (!isv && (wc & 1) == 0) {
;                                 const int tix = row < cfg::MP ? (row & 2047) : 2048 + (row & 3);
;                                 const f32x4 cs = *(const f32x4*)(ropec + tix * 8 + 4 * n), sn = *(const f32x4*)(ropes + tix * 8 + 4 * n);
; #pragma unroll
;                                 for (int i = 0; i < 4; ++i) { const float p = shx16(v[i], fq & 1); const float rv = v[i] * cs[i] + (fq == 0 ? -p : p) * sn[i]; v[i] = fq < 2 ? rv : v[i]; }
;                             }
;                             if (pn < 4) st_bf4(Q + (size_t)row * 512 + (pn - 2) * 256 + tc, v);
.Lsp_q1:
	s_nop 7
	v_mov_b32_e32 v173, v126
	v_mov_b32_e32 v205, v127
	v_mov_b32_e32 v204, v128
	v_mov_b32_e32 v206, v129
	v_lshl_add_u64 v[130:131], s[82:83], 0, v[174:175]
	v_lshl_add_u64 v[130:131], s[0:1], 1, v[130:131]
	v_lshlrev_b32_e32 v96, 1, v142
	v_lshl_add_u64 v[130:131], v[130:131], 0, v[96:97]
	v_cvt_pk_bf16_f32 v132, v173, v205
	v_cvt_pk_bf16_f32 v133, v204, v206
	global_store_dwordx2 v[130:131], v[132:133], off offset:-1024
	s_ashr_i32 s93, s0, 31
	s_mov_b32 s92, s0
	v_lshl_add_u64 v[130:131], s[30:31], 0, v[178:179]
	v_lshl_add_u64 v[132:133], s[92:93], 2, v[130:131]
	v_lshlrev_b32_e32 v130, 2, v142
	v_mov_b32_e32 v131, v122
	v_mov_b32_e32 v204, v123
	v_mov_b32_e32 v173, v124
	v_mov_b32_e32 v205, v125
	v_lshl_add_u64 v[126:127], s[82:83], 0, v[174:175]
	v_lshl_add_u64 v[126:127], s[0:1], 1, v[126:127]
	v_lshlrev_b32_e32 v96, 1, v142
	v_lshl_add_u64 v[126:127], v[126:127], 0, v[96:97]
	v_cvt_pk_bf16_f32 v128, v131, v204
	v_cvt_pk_bf16_f32 v129, v173, v205
	global_store_dwordx2 v[126:127], v[128:129], off offset:-1016
	v_readlane_b32 s70, v254, 59
	v_readlane_b32 s71, v254, 60
	v_mov_b32_e32 v131, v118
	v_mov_b32_e32 v184, v119
	v_mov_b32_e32 v173, v120
	v_mov_b32_e32 v185, v121
	v_lshl_add_u64 v[122:123], s[82:83], 0, v[174:175]
	v_lshl_add_u64 v[122:123], s[0:1], 1, v[122:123]
	v_lshlrev_b32_e32 v96, 1, v142
	v_lshl_add_u64 v[122:123], v[122:123], 0, v[96:97]
	v_cvt_pk_bf16_f32 v124, v131, v184
	v_cvt_pk_bf16_f32 v125, v173, v185
	global_store_dwordx2 v[122:123], v[124:125], off offset:-768
	v_mov_b32_e32 v128, v114
	v_mov_b32_e32 v131, v115
	v_mov_b32_e32 v129, v116
	v_mov_b32_e32 v173, v117
	s_mov_b64 s[70:71], -1
	s_andn2_b64 vcc, exec, s[70:71]
	v_lshl_add_u64 v[118:119], s[82:83], 0, v[174:175]
	v_lshl_add_u64 v[118:119], s[0:1], 1, v[118:119]
	v_lshlrev_b32_e32 v96, 1, v142
	v_lshl_add_u64 v[118:119], v[118:119], 0, v[96:97]
	v_cvt_pk_bf16_f32 v120, v128, v131
	v_cvt_pk_bf16_f32 v121, v129, v173
	global_store_dwordx2 v[118:119], v[120:121], off offset:-760
	v_or_b32_e32 v114, 16, v172
	v_mad_i64_i32 v[124:125], s[18:19], v114, s61, 0
	s_movk_i32 s18, 0x7df
	s_nop 0
	v_bitop3_b32 v96, v172, s18, 16 bitop3:0xc8
	s_movk_i32 s18, 0x4000
	v_cmp_gt_i32_e32 vcc, s18, v114
	s_nop 1
	v_cndmask_b32_e32 v116, v151, v96, vcc
	v_ashrrev_i32_e32 v115, 31, v114
	v_lshlrev_b32_e32 v176, 3, v116
	v_add_u32_e32 v116, 0xffffc010, v172
	v_lshlrev_b64 v[122:123], 11, v[114:115]
	v_lshrrev_b32_e32 v173, 2, v116
	v_lshlrev_b64 v[118:119], 10, v[114:115]
	v_mov_b32_e32 v131, v110
	v_mov_b32_e32 v178, v111
	v_mov_b32_e32 v177, v112
	v_mov_b32_e32 v179, v113
	v_lshl_add_u64 v[114:115], s[82:83], 0, v[118:119]
	v_lshl_add_u64 v[114:115], s[0:1], 1, v[114:115]
	v_lshlrev_b32_e32 v96, 1, v142
	v_lshl_add_u64 v[114:115], v[114:115], 0, v[96:97]
	v_cvt_pk_bf16_f32 v116, v131, v178
	v_cvt_pk_bf16_f32 v117, v177, v179
	global_store_dwordx2 v[114:115], v[116:117], off offset:-1024
	v_lshl_add_u64 v[114:115], s[30:31], 0, v[122:123]
	v_lshl_add_u64 v[114:115], s[92:93], 2, v[114:115]
	v_mov_b32_e32 v131, v106
	v_mov_b32_e32 v175, v107
	v_mov_b32_e32 v174, v108
	v_mov_b32_e32 v177, v109
	v_lshl_add_u64 v[110:111], s[82:83], 0, v[118:119]
	v_lshl_add_u64 v[110:111], s[0:1], 1, v[110:111]
	v_lshlrev_b32_e32 v96, 1, v142
	v_lshl_add_u64 v[110:111], v[110:111], 0, v[96:97]
	v_cvt_pk_bf16_f32 v112, v131, v175
	v_cvt_pk_bf16_f32 v113, v174, v177
	global_store_dwordx2 v[110:111], v[112:113], off offset:-1016
	v_mov_b32_e32 v126, v102
	v_mov_b32_e32 v128, v103
	v_mov_b32_e32 v127, v104
	v_mov_b32_e32 v129, v105
	v_lshl_add_u64 v[106:107], s[82:83], 0, v[118:119]
	v_lshl_add_u64 v[106:107], s[0:1], 1, v[106:107]
	v_lshlrev_b32_e32 v96, 1, v142
	v_lshl_add_u64 v[106:107], v[106:107], 0, v[96:97]
	v_cvt_pk_bf16_f32 v108, v126, v128
	v_cvt_pk_bf16_f32 v109, v127, v129
	global_store_dwordx2 v[106:107], v[108:109], off offset:-768
	v_mov_b32_e32 v112, v98
	v_mov_b32_e32 v116, v99
	v_mov_b32_e32 v113, v100
	v_mov_b32_e32 v117, v101
	s_mov_b64 s[70:71], -1
	s_andn2_b64 vcc, exec, s[70:71]
	v_lshl_add_u64 v[102:103], s[82:83], 0, v[118:119]
	v_lshl_add_u64 v[102:103], s[0:1], 1, v[102:103]
	v_lshlrev_b32_e32 v96, 1, v142
	v_lshl_add_u64 v[102:103], v[102:103], 0, v[96:97]
	v_cvt_pk_bf16_f32 v104, v112, v116
	v_cvt_pk_bf16_f32 v105, v113, v117
	global_store_dwordx2 v[102:103], v[104:105], off offset:-760
	v_or_b32_e32 v98, 32, v172
	v_mad_i64_i32 v[108:109], s[18:19], v98, s61, 0
	s_movk_i32 s18, 0x7ef
	s_nop 0
	v_bitop3_b32 v96, v172, s18, 32 bitop3:0xc8
	s_movk_i32 s18, 0x4000
	v_cmp_gt_i32_e32 vcc, s18, v98
	s_nop 1
	v_cndmask_b32_e32 v100, v151, v96, vcc
	v_ashrrev_i32_e32 v99, 31, v98
	v_lshlrev_b32_e32 v119, 3, v100
	v_add_u32_e32 v100, 0xffffc020, v172
	v_lshlrev_b64 v[106:107], 11, v[98:99]
	v_lshrrev_b32_e32 v118, 2, v100
	v_lshlrev_b64 v[102:103], 10, v[98:99]
	v_mov_b32_e32 v120, v92
	v_mov_b32_e32 v122, v93
	v_mov_b32_e32 v121, v94
	v_mov_b32_e32 v123, v95
	v_lshl_add_u64 v[98:99], s[82:83], 0, v[102:103]
	v_lshl_add_u64 v[98:99], s[0:1], 1, v[98:99]
	v_lshlrev_b32_e32 v96, 1, v142
	v_lshl_add_u64 v[98:99], v[98:99], 0, v[96:97]
	v_cvt_pk_bf16_f32 v100, v120, v122
	v_cvt_pk_bf16_f32 v101, v121, v123
	global_store_dwordx2 v[98:99], v[100:101], off offset:-1024
	v_lshl_add_u64 v[98:99], s[30:31], 0, v[106:107]
	v_lshl_add_u64 v[98:99], s[92:93], 2, v[98:99]
	v_mov_b32_e32 v116, v88
	v_mov_b32_e32 v120, v89
	v_mov_b32_e32 v117, v90
	v_mov_b32_e32 v121, v91
	v_lshl_add_u64 v[92:93], s[82:83], 0, v[102:103]
	v_lshl_add_u64 v[92:93], s[0:1], 1, v[92:93]
	v_lshlrev_b32_e32 v96, 1, v142
	v_lshl_add_u64 v[92:93], v[92:93], 0, v[96:97]
	v_cvt_pk_bf16_f32 v94, v116, v120
; __device__ __forceinline__ float shx16(float v, int odd  ) { const unsigned x = __builtin_bit_cast(unsigned, v); auto r = __builtin_amdgcn_permlane16_swap(x, x, false, false); return __builtin_bit_cast(float, odd ? r[0] : r[1]); }
; __device__ __forceinline__ unsigned cvt_pk_bf16(float lo, float hi) { unsigned r; asm volatile("v_cvt_pk_bf16_f32 %0, %1, %2" : "=v"(r) : "v"(lo), "v"(hi)); return r; }
; __device__ __forceinline__ void st_bf4(bf16_t* p, const f32x4 v) { u32x2 w; w.x = cvt_pk_bf16(v[0], v[1]); w.y = cvt_pk_bf16(v[2], v[3]); *(u32x2*)p = w; }
;     __device__ __forceinline__ void operator()(const f32x4 (&acc)[2][2][4][2], const Unit& u, int wr, int wc, int fr, int fq) const {
;     ...
;             for (int m = 0; m < 4; ++m) { const int row = u.pm * 256 + ai * 128 + wr * 64 + m * 16 + fr;
; #pragma unroll
;                 for (int bj = 0; bj < 2; ++bj)
; #pragma unroll
;                     for (int n = 0; n < 2; ++n) { const int tc = bj * 128 + wc * 32 + 8 * fq + 4 * n; f32x4 v = acc[ai][bj][m][n];
;                         if (pn < 2) { *(f32x4*)(XA + (size_t)row * 512 + pn * 256 + tc) = v; }
;                         else if (pn <= 4) {
;                             const bool isv = (pn == 4 && bj == 1);
;                             if (!isv && (wc & 1) == 0) {
;                                 const int tix = row < cfg::MP ? (row & 2047) : 2048 + (row & 3);
;                                 const f32x4 cs = *(const f32x4*)(ropec + tix * 8 + 4 * n), sn = *(const f32x4*)(ropes + tix * 8 + 4 * n);
; #pragma unroll
;                                 for (int i = 0; i < 4; ++i) { const float p = shx16(v[i], fq & 1); const float rv = v[i] * cs[i] + (fq == 0 ? -p : p) * sn[i]; v[i] = fq < 2 ? rv : v[i]; }
;                             }
;                             if (pn < 4) st_bf4(Q + (size_t)row * 512 + (pn - 2) * 256 + tc, v);
	v_cvt_pk_bf16_f32 v95, v117, v121
	global_store_dwordx2 v[92:93], v[94:95], off offset:-1016
	v_mov_b32_e32 v110, v84
	v_mov_b32_e32 v112, v85
	v_mov_b32_e32 v111, v86
	v_mov_b32_e32 v113, v87
	v_lshl_add_u64 v[88:89], s[82:83], 0, v[102:103]
	v_lshl_add_u64 v[88:89], s[0:1], 1, v[88:89]
	v_lshlrev_b32_e32 v96, 1, v142
	v_lshl_add_u64 v[88:89], v[88:89], 0, v[96:97]
	v_cvt_pk_bf16_f32 v90, v110, v112
	v_cvt_pk_bf16_f32 v91, v111, v113
	global_store_dwordx2 v[88:89], v[90:91], off offset:-768
	v_mov_b32_e32 v94, v80
	v_mov_b32_e32 v100, v81
	v_mov_b32_e32 v95, v82
	v_mov_b32_e32 v101, v83
	s_mov_b64 s[70:71], -1
	s_andn2_b64 vcc, exec, s[70:71]
	v_lshl_add_u64 v[84:85], s[82:83], 0, v[102:103]
	v_lshl_add_u64 v[84:85], s[0:1], 1, v[84:85]
	v_lshlrev_b32_e32 v96, 1, v142
	v_lshl_add_u64 v[84:85], v[84:85], 0, v[96:97]
	v_cvt_pk_bf16_f32 v86, v94, v100
	v_cvt_pk_bf16_f32 v87, v95, v101
	global_store_dwordx2 v[84:85], v[86:87], off offset:-760
	v_or_b32_e32 v80, 48, v172
	v_mad_i64_i32 v[90:91], s[18:19], v80, s61, 0
	s_movk_i32 s18, 0x7ff
	s_nop 0
	v_bitop3_b32 v82, v172, s18, 48 bitop3:0xc8
	s_movk_i32 s18, 0x4000
	v_cmp_gt_i32_e32 vcc, s18, v80
	v_ashrrev_i32_e32 v81, 31, v80
	s_nop 0
	v_cndmask_b32_e32 v83, v151, v82, vcc
	v_lshlrev_b32_e32 v103, 3, v83
	v_add_u32_e32 v83, 0xffffc030, v172
	v_lshrrev_b32_e32 v102, 2, v83
	v_lshlrev_b64 v[84:85], 10, v[80:81]
	v_mov_b32_e32 v104, v76
	v_mov_b32_e32 v106, v77
	v_mov_b32_e32 v105, v78
	v_mov_b32_e32 v107, v79
	v_lshl_add_u64 v[80:81], s[82:83], 0, v[84:85]
	v_lshl_add_u64 v[80:81], s[0:1], 1, v[80:81]
	v_lshlrev_b32_e32 v96, 1, v142
	v_lshl_add_u64 v[80:81], v[80:81], 0, v[96:97]
	v_cvt_pk_bf16_f32 v82, v104, v106
	v_cvt_pk_bf16_f32 v83, v105, v107
	global_store_dwordx2 v[80:81], v[82:83], off offset:-1024
	v_mov_b32_e32 v100, v72
	v_mov_b32_e32 v104, v73
	v_mov_b32_e32 v101, v74
	v_mov_b32_e32 v105, v75
	v_lshl_add_u64 v[76:77], s[82:83], 0, v[84:85]
	v_lshl_add_u64 v[76:77], s[0:1], 1, v[76:77]
	v_lshlrev_b32_e32 v96, 1, v142
	v_lshl_add_u64 v[76:77], v[76:77], 0, v[96:97]
	v_cvt_pk_bf16_f32 v78, v100, v104
	v_cvt_pk_bf16_f32 v79, v101, v105
	global_store_dwordx2 v[76:77], v[78:79], off offset:-1016
	v_mov_b32_e32 v92, v68
	v_mov_b32_e32 v94, v69
	v_mov_b32_e32 v93, v70
	v_mov_b32_e32 v95, v71
	v_lshl_add_u64 v[72:73], s[82:83], 0, v[84:85]
	v_lshl_add_u64 v[72:73], s[0:1], 1, v[72:73]
	v_lshlrev_b32_e32 v96, 1, v142
	v_lshl_add_u64 v[72:73], v[72:73], 0, v[96:97]
	v_cvt_pk_bf16_f32 v74, v92, v94
	v_cvt_pk_bf16_f32 v75, v93, v95
	global_store_dwordx2 v[72:73], v[74:75], off offset:-768
	v_mov_b32_e32 v78, v64
	v_mov_b32_e32 v82, v65
	v_mov_b32_e32 v79, v66
	v_mov_b32_e32 v83, v67
	s_mov_b64 s[70:71], -1
	s_andn2_b64 vcc, exec, s[70:71]
	v_lshl_add_u64 v[68:69], s[82:83], 0, v[84:85]
	v_lshl_add_u64 v[68:69], s[0:1], 1, v[68:69]
	v_lshlrev_b32_e32 v96, 1, v142
	v_lshl_add_u64 v[68:69], v[68:69], 0, v[96:97]
	v_cvt_pk_bf16_f32 v70, v78, v82
	v_cvt_pk_bf16_f32 v71, v79, v83
	global_store_dwordx2 v[68:69], v[70:71], off offset:-760
	s_add_i32 s46, s53, 0x80
	v_or_b32_e32 v68, s46, v143
	v_mad_i64_i32 v[76:77], s[18:19], v68, s61, 0
	v_mov_b32_e32 v64, 0x7cf
	s_movk_i32 s18, 0x4000
	v_bitop3_b32 v64, s46, v64, v143 bitop3:0xc8
	v_cmp_gt_i32_e32 vcc, s18, v68
	v_add_u32_e32 v96, 0xfffff880, v64
	v_ashrrev_i32_e32 v69, 31, v68
	v_cndmask_b32_e32 v65, v151, v64, vcc
	v_lshlrev_b32_e32 v87, 3, v65
	v_add_u32_e32 v65, 0xffffc000, v68
	v_lshlrev_b64 v[78:79], 7, v[96:97]
	s_mov_b64 s[70:71], 0x1080000
	v_lshlrev_b64 v[74:75], 11, v[68:69]
	v_lshrrev_b32_e32 v86, 2, v65
	v_lshlrev_b64 v[70:71], 10, v[68:69]
	v_lshl_add_u64 v[80:81], v[78:79], 0, s[70:71]
	s_mov_b32 s75, 0x400000
	v_mov_b32_e32 v69, v60
	v_mov_b32_e32 v89, v61
	v_mov_b32_e32 v88, v62
	v_mov_b32_e32 v90, v63
	v_lshl_add_u64 v[64:65], s[82:83], 0, v[70:71]
	v_lshl_add_u64 v[64:65], s[0:1], 1, v[64:65]
	v_lshlrev_b32_e32 v96, 1, v142
	v_lshl_add_u64 v[64:65], v[64:65], 0, v[96:97]
	v_cvt_pk_bf16_f32 v66, v69, v89
	v_cvt_pk_bf16_f32 v67, v88, v90
	global_store_dwordx2 v[64:65], v[66:67], off offset:-1024
	v_lshl_add_u64 v[64:65], s[30:31], 0, v[74:75]
	v_lshl_add_u64 v[64:65], s[92:93], 2, v[64:65]
	v_mov_b32_e32 v69, v56
	v_mov_b32_e32 v85, v57
	v_mov_b32_e32 v84, v58
	v_mov_b32_e32 v88, v59
	v_lshl_add_u64 v[60:61], s[82:83], 0, v[70:71]
	v_lshl_add_u64 v[60:61], s[0:1], 1, v[60:61]
	v_lshlrev_b32_e32 v96, 1, v142
	v_lshl_add_u64 v[60:61], v[60:61], 0, v[96:97]
	v_cvt_pk_bf16_f32 v62, v69, v85
	v_cvt_pk_bf16_f32 v63, v84, v88
	global_store_dwordx2 v[60:61], v[62:63], off offset:-1016
	v_mov_b32_e32 v69, v52
	v_mov_b32_e32 v79, v53
	v_mov_b32_e32 v78, v54
	v_mov_b32_e32 v80, v55
	v_lshl_add_u64 v[56:57], s[82:83], 0, v[70:71]
	v_lshl_add_u64 v[56:57], s[0:1], 1, v[56:57]
	v_lshlrev_b32_e32 v96, 1, v142
	v_lshl_add_u64 v[56:57], v[56:57], 0, v[96:97]
	v_cvt_pk_bf16_f32 v58, v69, v79
	v_cvt_pk_bf16_f32 v59, v78, v80
	global_store_dwordx2 v[56:57], v[58:59], off offset:-768
	v_mov_b32_e32 v62, v48
	v_mov_b32_e32 v66, v49
	v_mov_b32_e32 v63, v50
	v_mov_b32_e32 v67, v51
	s_mov_b64 s[70:71], -1
	s_andn2_b64 vcc, exec, s[70:71]
	v_lshl_add_u64 v[52:53], s[82:83], 0, v[70:71]
	v_lshl_add_u64 v[52:53], s[0:1], 1, v[52:53]
	v_lshlrev_b32_e32 v96, 1, v142
	v_lshl_add_u64 v[52:53], v[52:53], 0, v[96:97]
	v_cvt_pk_bf16_f32 v54, v62, v66
	v_cvt_pk_bf16_f32 v55, v63, v67
	global_store_dwordx2 v[52:53], v[54:55], off offset:-760
	v_or_b32_e32 v48, 16, v68
	v_mad_i64_i32 v[58:59], s[18:19], v48, s61, 0
	s_movk_i32 s18, 0x7df
	s_nop 0
	v_bitop3_b32 v50, v68, s18, 16 bitop3:0xc8
	s_movk_i32 s18, 0x4000
	v_cmp_gt_i32_e32 vcc, s18, v48
	v_ashrrev_i32_e32 v49, 31, v48
; __device__ __forceinline__ float shx16(float v, int odd  ) { const unsigned x = __builtin_bit_cast(unsigned, v); auto r = __builtin_amdgcn_permlane16_swap(x, x, false, false); return __builtin_bit_cast(float, odd ? r[0] : r[1]); }
; __device__ __forceinline__ unsigned cvt_pk_bf16(float lo, float hi) { unsigned r; asm volatile("v_cvt_pk_bf16_f32 %0, %1, %2" : "=v"(r) : "v"(lo), "v"(hi)); return r; }
; __device__ __forceinline__ void st_bf4(bf16_t* p, const f32x4 v) { u32x2 w; w.x = cvt_pk_bf16(v[0], v[1]); w.y = cvt_pk_bf16(v[2], v[3]); *(u32x2*)p = w; }
;     __device__ __forceinline__ void operator()(const f32x4 (&acc)[2][2][4][2], const Unit& u, int wr, int wc, int fr, int fq) const {
;     ...
;             for (int m = 0; m < 4; ++m) { const int row = u.pm * 256 + ai * 128 + wr * 64 + m * 16 + fr;
; #pragma unroll
;                 for (int bj = 0; bj < 2; ++bj)
; #pragma unroll
;                     for (int n = 0; n < 2; ++n) { const int tc = bj * 128 + wc * 32 + 8 * fq + 4 * n; f32x4 v = acc[ai][bj][m][n];
;                         if (pn < 2) { *(f32x4*)(XA + (size_t)row * 512 + pn * 256 + tc) = v; }
;                         else if (pn <= 4) {
;                             const bool isv = (pn == 4 && bj == 1);
;                             if (!isv && (wc & 1) == 0) {
;                                 const int tix = row < cfg::MP ? (row & 2047) : 2048 + (row & 3);
;                                 const f32x4 cs = *(const f32x4*)(ropec + tix * 8 + 4 * n), sn = *(const f32x4*)(ropes + tix * 8 + 4 * n);
; #pragma unroll
;                                 for (int i = 0; i < 4; ++i) { const float p = shx16(v[i], fq & 1); const float rv = v[i] * cs[i] + (fq == 0 ? -p : p) * sn[i]; v[i] = fq < 2 ? rv : v[i]; }
;                             }
;                             if (pn < 4) st_bf4(Q + (size_t)row * 512 + (pn - 2) * 256 + tc, v);
	s_nop 0
	v_cndmask_b32_e32 v51, v151, v50, vcc
	v_lshlrev_b32_e32 v70, 3, v51
	v_add_u32_e32 v51, 0xffffc010, v68
	v_lshlrev_b64 v[56:57], 11, v[48:49]
	v_lshrrev_b32_e32 v69, 2, v51
	v_lshlrev_b64 v[52:53], 10, v[48:49]
	v_mov_b32_e32 v71, v44
	v_mov_b32_e32 v73, v45
	v_mov_b32_e32 v72, v46
	v_mov_b32_e32 v74, v47
	v_lshl_add_u64 v[48:49], s[82:83], 0, v[52:53]
	v_lshl_add_u64 v[48:49], s[0:1], 1, v[48:49]
	v_lshlrev_b32_e32 v96, 1, v142
	v_lshl_add_u64 v[48:49], v[48:49], 0, v[96:97]
	v_cvt_pk_bf16_f32 v50, v71, v73
	v_cvt_pk_bf16_f32 v51, v72, v74
	global_store_dwordx2 v[48:49], v[50:51], off offset:-1024
	v_lshl_add_u64 v[48:49], s[30:31], 0, v[56:57]
	v_lshl_add_u64 v[48:49], s[92:93], 2, v[48:49]
	v_mov_b32_e32 v66, v40
	v_mov_b32_e32 v71, v41
	v_mov_b32_e32 v67, v42
	v_mov_b32_e32 v72, v43
	v_lshl_add_u64 v[44:45], s[82:83], 0, v[52:53]
	v_lshl_add_u64 v[44:45], s[0:1], 1, v[44:45]
	v_lshlrev_b32_e32 v96, 1, v142
	v_lshl_add_u64 v[44:45], v[44:45], 0, v[96:97]
	v_cvt_pk_bf16_f32 v46, v66, v71
	v_cvt_pk_bf16_f32 v47, v67, v72
	global_store_dwordx2 v[44:45], v[46:47], off offset:-1016
	v_mov_b32_e32 v60, v36
	v_mov_b32_e32 v62, v37
	v_mov_b32_e32 v61, v38
	v_mov_b32_e32 v63, v39
	v_lshl_add_u64 v[40:41], s[82:83], 0, v[52:53]
	v_lshl_add_u64 v[40:41], s[0:1], 1, v[40:41]
	v_lshlrev_b32_e32 v96, 1, v142
	v_lshl_add_u64 v[40:41], v[40:41], 0, v[96:97]
	v_cvt_pk_bf16_f32 v42, v60, v62
	v_cvt_pk_bf16_f32 v43, v61, v63
	global_store_dwordx2 v[40:41], v[42:43], off offset:-768
	v_mov_b32_e32 v46, v32
	v_mov_b32_e32 v50, v33
	v_mov_b32_e32 v47, v34
	v_mov_b32_e32 v51, v35
	s_mov_b64 s[70:71], -1
	s_andn2_b64 vcc, exec, s[70:71]
	v_lshl_add_u64 v[36:37], s[82:83], 0, v[52:53]
	v_lshl_add_u64 v[36:37], s[0:1], 1, v[36:37]
	v_lshlrev_b32_e32 v96, 1, v142
	v_lshl_add_u64 v[36:37], v[36:37], 0, v[96:97]
	v_cvt_pk_bf16_f32 v38, v46, v50
	v_cvt_pk_bf16_f32 v39, v47, v51
	global_store_dwordx2 v[36:37], v[38:39], off offset:-760
	v_or_b32_e32 v32, 32, v68
	v_mad_i64_i32 v[42:43], s[18:19], v32, s61, 0
	s_movk_i32 s18, 0x7ef
	s_nop 0
	v_bitop3_b32 v34, v68, s18, 32 bitop3:0xc8
	s_movk_i32 s18, 0x4000
	v_cmp_gt_i32_e32 vcc, s18, v32
	v_ashrrev_i32_e32 v33, 31, v32
	s_nop 0
	v_cndmask_b32_e32 v35, v151, v34, vcc
	v_lshlrev_b32_e32 v53, 3, v35
	v_add_u32_e32 v35, 0xffffc020, v68
	v_lshlrev_b64 v[40:41], 11, v[32:33]
	v_lshrrev_b32_e32 v52, 2, v35
	v_lshlrev_b64 v[36:37], 10, v[32:33]
	v_mov_b32_e32 v54, v28
	v_mov_b32_e32 v56, v29
	v_mov_b32_e32 v55, v30
	v_mov_b32_e32 v57, v31
	v_lshl_add_u64 v[32:33], s[82:83], 0, v[36:37]
	v_lshl_add_u64 v[32:33], s[0:1], 1, v[32:33]
	v_lshlrev_b32_e32 v96, 1, v142
	v_lshl_add_u64 v[32:33], v[32:33], 0, v[96:97]
	v_cvt_pk_bf16_f32 v34, v54, v56
	v_cvt_pk_bf16_f32 v35, v55, v57
	global_store_dwordx2 v[32:33], v[34:35], off offset:-1024
	v_lshl_add_u64 v[32:33], s[30:31], 0, v[40:41]
	v_lshl_add_u64 v[32:33], s[92:93], 2, v[32:33]
	v_mov_b32_e32 v50, v24
	v_mov_b32_e32 v54, v25
	v_mov_b32_e32 v51, v26
	v_mov_b32_e32 v55, v27
	v_lshl_add_u64 v[28:29], s[82:83], 0, v[36:37]
	v_lshl_add_u64 v[28:29], s[0:1], 1, v[28:29]
	v_lshlrev_b32_e32 v96, 1, v142
	v_lshl_add_u64 v[28:29], v[28:29], 0, v[96:97]
	v_cvt_pk_bf16_f32 v30, v50, v54
	v_cvt_pk_bf16_f32 v31, v51, v55
	global_store_dwordx2 v[28:29], v[30:31], off offset:-1016
	v_mov_b32_e32 v44, v20
	v_mov_b32_e32 v46, v21
	v_mov_b32_e32 v45, v22
	v_mov_b32_e32 v47, v23
	v_lshl_add_u64 v[24:25], s[82:83], 0, v[36:37]
	v_lshl_add_u64 v[24:25], s[0:1], 1, v[24:25]
	v_lshlrev_b32_e32 v96, 1, v142
	v_lshl_add_u64 v[24:25], v[24:25], 0, v[96:97]
	v_cvt_pk_bf16_f32 v26, v44, v46
	v_cvt_pk_bf16_f32 v27, v45, v47
	global_store_dwordx2 v[24:25], v[26:27], off offset:-768
	v_mov_b32_e32 v30, v16
	v_mov_b32_e32 v34, v17
	v_mov_b32_e32 v31, v18
	v_mov_b32_e32 v35, v19
	s_mov_b64 s[70:71], -1
	s_andn2_b64 vcc, exec, s[70:71]
	v_lshl_add_u64 v[20:21], s[82:83], 0, v[36:37]
	v_lshl_add_u64 v[20:21], s[0:1], 1, v[20:21]
	v_lshlrev_b32_e32 v96, 1, v142
	v_lshl_add_u64 v[20:21], v[20:21], 0, v[96:97]
	v_cvt_pk_bf16_f32 v22, v30, v34
	v_cvt_pk_bf16_f32 v23, v31, v35
	global_store_dwordx2 v[20:21], v[22:23], off offset:-760
	v_or_b32_e32 v16, 48, v68
	v_mad_i64_i32 v[26:27], s[18:19], v16, s61, 0
	s_movk_i32 s18, 0x3fff
	s_nop 0
	v_cmp_lt_i32_e64 s[20:21], s18, v16
	s_movk_i32 s18, 0x7ff
	v_bitop3_b32 v18, v68, s18, 48 bitop3:0xc8
	s_movk_i32 s18, 0x4000
	v_cmp_gt_i32_e32 vcc, s18, v16
	v_add_u32_e32 v96, 0xfffff880, v18
	v_ashrrev_i32_e32 v17, 31, v16
	v_cndmask_b32_e32 v19, v151, v18, vcc
	v_lshlrev_b32_e32 v37, 3, v19
	v_add_u32_e32 v19, 0xffffc030, v68
	v_lshlrev_b64 v[28:29], 7, v[96:97]
	v_lshlrev_b64 v[24:25], 11, v[16:17]
	v_lshlrev_b64 v[22:23], 8, v[16:17]
	v_lshrrev_b32_e32 v36, 2, v19
	v_lshlrev_b64 v[20:21], 10, v[16:17]
	v_mov_b32_e32 v38, v12
	v_mov_b32_e32 v40, v13
	v_mov_b32_e32 v39, v14
	v_mov_b32_e32 v41, v15
	v_lshl_add_u64 v[16:17], s[82:83], 0, v[20:21]
	v_lshl_add_u64 v[16:17], s[0:1], 1, v[16:17]
	v_lshlrev_b32_e32 v96, 1, v142
	v_lshl_add_u64 v[16:17], v[16:17], 0, v[96:97]
	v_cvt_pk_bf16_f32 v18, v38, v40
	v_cvt_pk_bf16_f32 v19, v39, v41
	global_store_dwordx2 v[16:17], v[18:19], off offset:-1024
	v_lshl_add_u64 v[16:17], s[30:31], 0, v[24:25]
	v_lshl_add_u64 v[16:17], s[92:93], 2, v[16:17]
	v_mov_b32_e32 v34, v8
	v_mov_b32_e32 v38, v9
	v_mov_b32_e32 v35, v10
	v_mov_b32_e32 v39, v11
	v_lshl_add_u64 v[12:13], s[82:83], 0, v[20:21]
	v_lshl_add_u64 v[12:13], s[0:1], 1, v[12:13]
	v_lshlrev_b32_e32 v96, 1, v142
	v_lshl_add_u64 v[12:13], v[12:13], 0, v[96:97]
	v_cvt_pk_bf16_f32 v14, v34, v38
	v_cvt_pk_bf16_f32 v15, v35, v39
	global_store_dwordx2 v[12:13], v[14:15], off offset:-1016
	s_mov_b64 s[70:71], 0x1100000
	v_lshl_add_u64 v[12:13], v[28:29], 0, s[70:71]
	v_mov_b32_e32 v28, v4
	v_mov_b32_e32 v30, v5
	v_mov_b32_e32 v29, v6
	v_mov_b32_e32 v31, v7
	v_lshl_add_u64 v[8:9], s[82:83], 0, v[20:21]
	v_lshl_add_u64 v[8:9], s[0:1], 1, v[8:9]
	v_lshlrev_b32_e32 v96, 1, v142
	v_lshl_add_u64 v[8:9], v[8:9], 0, v[96:97]
	v_cvt_pk_bf16_f32 v10, v28, v30
	v_cvt_pk_bf16_f32 v11, v29, v31
	global_store_dwordx2 v[8:9], v[10:11], off offset:-768
	s_mov_b32 s70, 0x1200000
	s_mov_b32 s71, 0x1400000
	v_mov_b32_e32 v14, v0
	v_mov_b32_e32 v18, v1
	v_mov_b32_e32 v15, v2
	v_mov_b32_e32 v19, v3
	s_mov_b64 s[14:15], -1
	v_lshl_add_u64 v[4:5], s[82:83], 0, v[20:21]
	v_lshl_add_u64 v[4:5], s[0:1], 1, v[4:5]
	v_lshlrev_b32_e32 v96, 1, v142
	v_lshl_add_u64 v[4:5], v[4:5], 0, v[96:97]
	v_cvt_pk_bf16_f32 v6, v14, v18
	v_cvt_pk_bf16_f32 v7, v15, v19
	global_store_dwordx2 v[4:5], v[6:7], off offset:-760
	s_branch .LBB0_1574
